# small per-row statistic stores (ssq / vstat partials) made write-through (sc0 sc1) to shorten the barrier's L2 write-back; on top of v82
# baseline (speedup 1.0000x reference)
.LBB0_150:
	s_mov_b32 s6, -1
	s_lshl_b32 s5, s5, 8
	v_mbcnt_lo_u32_b32 v128, s6, 0
	v_mbcnt_hi_u32_b32 v128, s6, v128
	s_getreg_b32 s6, hwreg(HW_REG_HW_ID, 0, 6)
	s_and_b32 s6, s6, 63
	s_lshl_b32 s6, s6, 2
	s_add_i32 s6, s6, 0
	s_add_i32 s6, s6, 0x20200
	v_mov_b32_e32 v129, s6
	ds_read_b32 v129, v129
	v_bfrev_b32_e32 v130, 0.5
	s_movk_i32 s84, 0x80
	s_lshl_b32 s74, s4, 2
	s_ashr_i32 s75, s74, 31
	s_waitcnt lgkmcnt(0)
	v_readfirstlane_b32 s6, v129
	s_nop 1
	v_lshl_add_u32 v128, s6, 6, v128
	s_nop 0
	v_readfirstlane_b32 s6, v128
	s_bfe_u32 s8, s6, 0x20006
	s_ashr_i32 s6, s6, 2
	s_andn2_b32 s6, s6, 63
	s_add_i32 s6, s6, s5
	v_and_or_b32 v170, v128, 15, s6
	s_lshl_b32 s5, s4, 8
	s_lshl_b32 s6, s8, 5
	v_bfe_u32 v129, v128, 4, 2
	s_or_b32 s5, s6, s5
	v_lshl_or_b32 v168, v129, 3, s5
	v_ashrrev_i32_e32 v169, 31, v168
	v_lshlrev_b64 v[146:147], 1, v[168:169]
	v_ashrrev_i32_e32 v171, 31, v170
	v_lshlrev_b32_e32 v128, 2, v128
	v_lshl_add_u64 v[172:173], s[68:69], 0, v[146:147]
	v_lshlrev_b64 v[148:149], 11, v[170:171]
	v_bitop3_b32 v180, v128, 64, v130 bitop3:0x6c
	v_bitop3_b32 v181, v128, s84, v130 bitop3:0x6c
	v_cmp_eq_u32_e32 vcc, 0, v129
	v_lshl_add_u64 v[128:129], v[172:173], 0, v[148:149]
	global_load_dwordx4 v[142:145], v[128:129], off
	global_load_dwordx4 v[136:139], v[128:129], off offset:256
	v_or_b32_e32 v174, 16, v170
	v_ashrrev_i32_e32 v175, 31, v174
	v_lshlrev_b64 v[176:177], 11, v[174:175]
	v_lshl_add_u64 v[128:129], v[172:173], 0, v[176:177]
	global_load_dwordx4 v[132:135], v[128:129], off
	s_nop 0
	global_load_dwordx4 v[128:131], v[128:129], off offset:256
	s_waitcnt vmcnt(0)
	v_lshlrev_b32_e32 v150, 16, v142
	v_and_b32_e32 v151, 0xffff0000, v142
	v_lshlrev_b32_e32 v142, 16, v143
	v_and_b32_e32 v143, 0xffff0000, v143
	v_lshlrev_b32_e32 v152, 16, v144
	v_and_b32_e32 v153, 0xffff0000, v144
	v_lshlrev_b32_e32 v144, 16, v145
	v_and_b32_e32 v145, 0xffff0000, v145
	v_pk_add_f32 v[124:125], v[124:125], v[150:151]
	v_pk_add_f32 v[126:127], v[126:127], v[142:143]
	v_pk_add_f32 v[142:143], v[122:123], v[144:145]
	v_pk_add_f32 v[122:123], v[120:121], v[152:153]
	v_cvt_pk_bf16_f32 v120, v124, v125
	v_lshl_add_u64 v[124:125], s[68:69], 0, v[148:149]
	v_lshl_add_u64 v[124:125], v[124:125], 0, v[146:147]
	v_cvt_pk_bf16_f32 v121, v126, v127
	v_cvt_pk_bf16_f32 v122, v122, v123
	v_cvt_pk_bf16_f32 v123, v142, v143
	global_store_dwordx4 v[124:125], v[120:123], off nt
	v_lshlrev_b32_e32 v126, 16, v120
	v_and_b32_e32 v127, 0xffff0000, v138
	v_and_b32_e32 v120, 0xffff0000, v120
	v_mul_f32_e32 v120, v120, v120
	v_fmac_f32_e32 v120, v126, v126
	v_lshlrev_b32_e32 v126, 16, v121
	v_and_b32_e32 v121, 0xffff0000, v121
	v_mul_f32_e32 v121, v121, v121
	v_fmac_f32_e32 v121, v126, v126
	v_add_f32_e32 v120, v120, v121
	v_lshlrev_b32_e32 v121, 16, v122
	v_and_b32_e32 v122, 0xffff0000, v122
	v_mul_f32_e32 v122, v122, v122
	v_fmac_f32_e32 v122, v121, v121
	v_add_f32_e32 v120, v120, v122
	v_and_b32_e32 v122, 0xffff0000, v123
	v_lshlrev_b32_e32 v121, 16, v123
	v_mul_f32_e32 v122, v122, v122
	v_fmac_f32_e32 v122, v121, v121
	v_add_f32_e32 v142, v120, v122
	v_lshlrev_b32_e32 v120, 16, v136
	v_and_b32_e32 v121, 0xffff0000, v136
	v_lshlrev_b32_e32 v122, 16, v137
	v_and_b32_e32 v123, 0xffff0000, v137
	v_lshlrev_b32_e32 v126, 16, v138
	v_lshlrev_b32_e32 v136, 16, v139
	v_and_b32_e32 v137, 0xffff0000, v139
	v_pk_add_f32 v[116:117], v[116:117], v[120:121]
	v_pk_add_f32 v[120:121], v[114:115], v[136:137]
	v_pk_add_f32 v[114:115], v[112:113], v[126:127]
	v_cvt_pk_bf16_f32 v112, v116, v117
	v_pk_add_f32 v[118:119], v[118:119], v[122:123]
	v_lshlrev_b32_e32 v116, 16, v112
	v_cvt_pk_bf16_f32 v113, v118, v119
	v_cvt_pk_bf16_f32 v114, v114, v115
	v_cvt_pk_bf16_f32 v115, v120, v121
	global_store_dwordx4 v[124:125], v[112:115], off offset:256 nt
	s_nop 1
	v_and_b32_e32 v112, 0xffff0000, v112
	v_mul_f32_e32 v112, v112, v112
	v_fmac_f32_e32 v112, v116, v116
	v_lshlrev_b32_e32 v116, 16, v113
	v_and_b32_e32 v113, 0xffff0000, v113
	v_mul_f32_e32 v113, v113, v113
	v_add_f32_e32 v112, v142, v112
	v_fmac_f32_e32 v113, v116, v116
	v_add_f32_e32 v112, v112, v113
	v_lshlrev_b32_e32 v113, 16, v114
	v_and_b32_e32 v114, 0xffff0000, v114
	v_mul_f32_e32 v114, v114, v114
	v_fmac_f32_e32 v114, v113, v113
	v_add_f32_e32 v112, v112, v114
	v_and_b32_e32 v114, 0xffff0000, v115
	v_lshlrev_b32_e32 v113, 16, v115
	v_mul_f32_e32 v114, v114, v114
	v_fmac_f32_e32 v114, v113, v113
	v_add_f32_e32 v112, v112, v114
	v_mov_b32_e32 v113, v112
	s_nop 1
	v_permlane16_swap_b32_e32 v113, v112
	s_waitcnt lgkmcnt(0)
	v_add_f32_e32 v112, v112, v113
	v_mov_b32_e32 v113, v112
	s_nop 1
	v_permlane32_swap_b32_e32 v113, v112
	s_and_saveexec_b64 s[6:7], vcc
	s_cbranch_execz .LBB0_152
	s_waitcnt lgkmcnt(0)
	v_add_f32_e32 v114, v112, v113
	v_lshlrev_b64 v[112:113], 6, v[170:171]
	v_lshl_add_u64 v[112:113], s[48:49], 0, v[112:113]
	v_lshl_add_u64 v[112:113], s[74:75], 2, v[112:113]
	s_lshl_b32 s38, s8, 2
	v_lshl_add_u64 v[112:113], v[112:113], 0, s[38:39]
	flat_store_dword v[112:113], v114 sc0 sc1
.LBB0_152:
	s_or_b64 exec, exec, s[6:7]
	v_lshlrev_b32_e32 v112, 16, v132
	s_waitcnt lgkmcnt(0)
	v_and_b32_e32 v113, 0xffff0000, v132
	v_lshlrev_b32_e32 v116, 16, v134
	v_and_b32_e32 v117, 0xffff0000, v134
	v_lshlrev_b32_e32 v118, 16, v135
	v_and_b32_e32 v119, 0xffff0000, v135
	v_pk_add_f32 v[108:109], v[108:109], v[112:113]
	v_lshlrev_b32_e32 v114, 16, v133
	v_and_b32_e32 v115, 0xffff0000, v133
	v_pk_add_f32 v[112:113], v[106:107], v[118:119]
	v_pk_add_f32 v[106:107], v[104:105], v[116:117]
	v_cvt_pk_bf16_f32 v104, v108, v109
	v_lshl_add_u64 v[108:109], s[68:69], 0, v[176:177]
	v_pk_add_f32 v[110:111], v[110:111], v[114:115]
	v_lshl_add_u64 v[108:109], v[168:169], 1, v[108:109]
	v_cvt_pk_bf16_f32 v105, v110, v111
	v_cvt_pk_bf16_f32 v106, v106, v107
	v_cvt_pk_bf16_f32 v107, v112, v113
	global_store_dwordx4 v[108:109], v[104:107], off nt
	v_lshlrev_b32_e32 v110, 16, v104
	v_and_b32_e32 v111, 0xffff0000, v130
	v_and_b32_e32 v104, 0xffff0000, v104
	v_mul_f32_e32 v104, v104, v104
	v_fmac_f32_e32 v104, v110, v110
	v_lshlrev_b32_e32 v110, 16, v105
	v_and_b32_e32 v105, 0xffff0000, v105
	v_mul_f32_e32 v105, v105, v105
	v_fmac_f32_e32 v105, v110, v110
	v_add_f32_e32 v104, v104, v105
	v_lshlrev_b32_e32 v105, 16, v106
	v_and_b32_e32 v106, 0xffff0000, v106
	v_mul_f32_e32 v106, v106, v106
	v_fmac_f32_e32 v106, v105, v105
	v_add_f32_e32 v104, v104, v106
	v_and_b32_e32 v106, 0xffff0000, v107
	v_lshlrev_b32_e32 v105, 16, v107
	v_mul_f32_e32 v106, v106, v106
	v_fmac_f32_e32 v106, v105, v105
	v_add_f32_e32 v114, v104, v106
	v_lshlrev_b32_e32 v104, 16, v128
	v_and_b32_e32 v105, 0xffff0000, v128
	v_lshlrev_b32_e32 v110, 16, v130
	v_lshlrev_b32_e32 v106, 16, v129
	v_and_b32_e32 v107, 0xffff0000, v129
	v_lshlrev_b32_e32 v112, 16, v131
	v_and_b32_e32 v113, 0xffff0000, v131
	v_pk_add_f32 v[100:101], v[100:101], v[104:105]
	v_pk_add_f32 v[96:97], v[96:97], v[110:111]
	v_pk_add_f32 v[102:103], v[102:103], v[106:107]
	v_pk_add_f32 v[104:105], v[98:99], v[112:113]
	v_cvt_pk_bf16_f32 v98, v100, v101
	v_cvt_pk_bf16_f32 v99, v102, v103
	v_cvt_pk_bf16_f32 v100, v96, v97
	s_nop 0
	v_and_b32_e32 v97, 0xffff0000, v98
	v_lshlrev_b32_e32 v96, 16, v98
	v_mul_f32_e32 v97, v97, v97
	v_fmac_f32_e32 v97, v96, v96
	v_and_b32_e32 v102, 0xffff0000, v99
	v_add_f32_e32 v96, v114, v97
	v_lshlrev_b32_e32 v97, 16, v99
	v_mul_f32_e32 v102, v102, v102
	v_fmac_f32_e32 v102, v97, v97
	v_add_f32_e32 v96, v96, v102
	v_and_b32_e32 v102, 0xffff0000, v100
	v_lshlrev_b32_e32 v97, 16, v100
	v_mul_f32_e32 v102, v102, v102
	v_fmac_f32_e32 v102, v97, v97
	v_cvt_pk_bf16_f32 v101, v104, v105
	v_add_f32_e32 v96, v96, v102
	v_and_b32_e32 v102, 0xffff0000, v101
	v_lshlrev_b32_e32 v97, 16, v101
	v_mul_f32_e32 v102, v102, v102
	v_fmac_f32_e32 v102, v97, v97
	v_add_f32_e32 v96, v96, v102
	v_mov_b32_e32 v97, v96
	s_nop 1
	v_permlane16_swap_b32_e32 v97, v96
	global_store_dwordx4 v[108:109], v[98:101], off offset:256 nt
	s_waitcnt lgkmcnt(0)
	v_add_f32_e32 v96, v96, v97
	v_mov_b32_e32 v97, v96
	s_nop 1
	v_permlane32_swap_b32_e32 v97, v96
	s_and_saveexec_b64 s[6:7], vcc
	s_cbranch_execz .LBB0_154
	s_waitcnt lgkmcnt(0)
	v_add_f32_e32 v98, v96, v97
	v_lshlrev_b64 v[96:97], 6, v[174:175]
	v_lshl_add_u64 v[96:97], s[48:49], 0, v[96:97]
	v_lshl_add_u64 v[96:97], s[74:75], 2, v[96:97]
	s_lshl_b32 s38, s8, 2
	v_lshl_add_u64 v[96:97], v[96:97], 0, s[38:39]
	flat_store_dword v[96:97], v98 sc0 sc1
.LBB0_154:
	s_or_b64 exec, exec, s[6:7]
	v_or_b32_e32 v112, 32, v170
	v_ashrrev_i32_e32 v113, 31, v112
	v_lshlrev_b64 v[118:119], 11, v[112:113]
	s_waitcnt lgkmcnt(0)
	v_lshl_add_u64 v[96:97], v[172:173], 0, v[118:119]
	global_load_dwordx4 v[114:117], v[96:97], off
	global_load_dwordx4 v[104:107], v[96:97], off offset:256
	v_or_b32_e32 v108, 48, v170
	v_ashrrev_i32_e32 v109, 31, v108
	v_lshlrev_b64 v[110:111], 11, v[108:109]
	v_lshl_add_u64 v[96:97], v[172:173], 0, v[110:111]
	global_load_dwordx4 v[100:103], v[96:97], off
	s_nop 0
	global_load_dwordx4 v[96:99], v[96:97], off offset:256
	s_waitcnt vmcnt(0)
	v_lshlrev_b32_e32 v120, 16, v114
	v_and_b32_e32 v121, 0xffff0000, v114
	v_lshlrev_b32_e32 v114, 16, v115
	v_and_b32_e32 v115, 0xffff0000, v115
	v_lshlrev_b32_e32 v122, 16, v116
	v_and_b32_e32 v123, 0xffff0000, v116
	v_lshlrev_b32_e32 v116, 16, v117
	v_and_b32_e32 v117, 0xffff0000, v117
	v_pk_add_f32 v[92:93], v[92:93], v[120:121]
	v_pk_add_f32 v[94:95], v[94:95], v[114:115]
	v_pk_add_f32 v[114:115], v[90:91], v[116:117]
	v_pk_add_f32 v[90:91], v[88:89], v[122:123]
	v_cvt_pk_bf16_f32 v88, v92, v93
	v_lshl_add_u64 v[92:93], s[68:69], 0, v[118:119]
	v_lshl_add_u64 v[92:93], v[168:169], 1, v[92:93]
	v_cvt_pk_bf16_f32 v89, v94, v95
	v_cvt_pk_bf16_f32 v90, v90, v91
	v_cvt_pk_bf16_f32 v91, v114, v115
	global_store_dwordx4 v[92:93], v[88:91], off nt
	v_lshlrev_b32_e32 v94, 16, v88
	v_and_b32_e32 v95, 0xffff0000, v106
	v_and_b32_e32 v88, 0xffff0000, v88
	v_mul_f32_e32 v88, v88, v88
	v_fmac_f32_e32 v88, v94, v94
	v_lshlrev_b32_e32 v94, 16, v89
	v_and_b32_e32 v89, 0xffff0000, v89
	v_mul_f32_e32 v89, v89, v89
	v_fmac_f32_e32 v89, v94, v94
	v_add_f32_e32 v88, v88, v89
	v_lshlrev_b32_e32 v89, 16, v90
	v_and_b32_e32 v90, 0xffff0000, v90
	v_mul_f32_e32 v90, v90, v90
	v_fmac_f32_e32 v90, v89, v89
	v_add_f32_e32 v88, v88, v90
	v_and_b32_e32 v90, 0xffff0000, v91
	v_lshlrev_b32_e32 v89, 16, v91
	v_mul_f32_e32 v90, v90, v90
	v_fmac_f32_e32 v90, v89, v89
	v_add_f32_e32 v114, v88, v90
	v_lshlrev_b32_e32 v88, 16, v104
	v_and_b32_e32 v89, 0xffff0000, v104
	v_lshlrev_b32_e32 v90, 16, v105
	v_and_b32_e32 v91, 0xffff0000, v105
	v_lshlrev_b32_e32 v94, 16, v106
	v_lshlrev_b32_e32 v104, 16, v107
	v_and_b32_e32 v105, 0xffff0000, v107
	v_pk_add_f32 v[84:85], v[84:85], v[88:89]
	v_pk_add_f32 v[88:89], v[82:83], v[104:105]
	v_pk_add_f32 v[82:83], v[80:81], v[94:95]
	v_cvt_pk_bf16_f32 v80, v84, v85
	v_pk_add_f32 v[86:87], v[86:87], v[90:91]
	v_lshlrev_b32_e32 v84, 16, v80
	v_cvt_pk_bf16_f32 v81, v86, v87
	v_cvt_pk_bf16_f32 v82, v82, v83
	v_cvt_pk_bf16_f32 v83, v88, v89
	global_store_dwordx4 v[92:93], v[80:83], off offset:256 nt
	s_nop 1
	v_and_b32_e32 v80, 0xffff0000, v80
	v_mul_f32_e32 v80, v80, v80
	v_fmac_f32_e32 v80, v84, v84
	v_lshlrev_b32_e32 v84, 16, v81
	v_and_b32_e32 v81, 0xffff0000, v81
	v_mul_f32_e32 v81, v81, v81
	v_add_f32_e32 v80, v114, v80
	v_fmac_f32_e32 v81, v84, v84
	v_add_f32_e32 v80, v80, v81
	v_lshlrev_b32_e32 v81, 16, v82
	v_and_b32_e32 v82, 0xffff0000, v82
	v_mul_f32_e32 v82, v82, v82
	v_fmac_f32_e32 v82, v81, v81
	v_add_f32_e32 v80, v80, v82
	v_and_b32_e32 v82, 0xffff0000, v83
	v_lshlrev_b32_e32 v81, 16, v83
	v_mul_f32_e32 v82, v82, v82
	v_fmac_f32_e32 v82, v81, v81
	v_add_f32_e32 v80, v80, v82
	v_mov_b32_e32 v81, v80
	s_nop 1
	v_permlane16_swap_b32_e32 v81, v80
	s_waitcnt lgkmcnt(0)
	v_add_f32_e32 v80, v80, v81
	v_mov_b32_e32 v81, v80
	s_nop 1
	v_permlane32_swap_b32_e32 v81, v80
	s_mov_b64 s[6:7], exec
	s_and_b64 s[4:5], s[6:7], vcc
	v_mov_b32_e32 v198, v216
	v_mov_b32_e32 v199, v217
	v_mov_b32_e32 v248, v218
	v_mov_b32_e32 v205, v219
	v_mov_b32_e32 v196, v220
	s_mov_b64 exec, s[4:5]
	s_cbranch_execz .LBB0_156
	s_waitcnt lgkmcnt(0)
	v_add_f32_e32 v82, v80, v81
	v_lshlrev_b64 v[80:81], 6, v[112:113]
	v_lshl_add_u64 v[80:81], s[48:49], 0, v[80:81]
	v_lshl_add_u64 v[80:81], s[74:75], 2, v[80:81]
	s_lshl_b32 s38, s8, 2
	v_lshl_add_u64 v[80:81], v[80:81], 0, s[38:39]
	flat_store_dword v[80:81], v82 sc0 sc1
.LBB0_156:
	s_or_b64 exec, exec, s[6:7]
	v_lshlrev_b32_e32 v80, 16, v100
	s_waitcnt lgkmcnt(0)
	v_and_b32_e32 v81, 0xffff0000, v100
	v_lshlrev_b32_e32 v84, 16, v102
	v_and_b32_e32 v85, 0xffff0000, v102
	v_lshlrev_b32_e32 v86, 16, v103
	v_and_b32_e32 v87, 0xffff0000, v103
	v_pk_add_f32 v[76:77], v[76:77], v[80:81]
	v_lshlrev_b32_e32 v82, 16, v101
	v_and_b32_e32 v83, 0xffff0000, v101
	v_pk_add_f32 v[80:81], v[74:75], v[86:87]
	v_pk_add_f32 v[74:75], v[72:73], v[84:85]
	v_cvt_pk_bf16_f32 v72, v76, v77
	v_lshl_add_u64 v[76:77], s[68:69], 0, v[110:111]
	v_pk_add_f32 v[78:79], v[78:79], v[82:83]
	v_lshl_add_u64 v[76:77], v[168:169], 1, v[76:77]
	v_cvt_pk_bf16_f32 v73, v78, v79
	v_cvt_pk_bf16_f32 v74, v74, v75
	v_cvt_pk_bf16_f32 v75, v80, v81
	global_store_dwordx4 v[76:77], v[72:75], off nt
	v_lshlrev_b32_e32 v78, 16, v72
	v_and_b32_e32 v79, 0xffff0000, v98
	v_and_b32_e32 v72, 0xffff0000, v72
	v_mul_f32_e32 v72, v72, v72
	v_fmac_f32_e32 v72, v78, v78
	v_lshlrev_b32_e32 v78, 16, v73
	v_and_b32_e32 v73, 0xffff0000, v73
	v_mul_f32_e32 v73, v73, v73
	v_fmac_f32_e32 v73, v78, v78
	v_add_f32_e32 v72, v72, v73
	v_lshlrev_b32_e32 v73, 16, v74
	v_and_b32_e32 v74, 0xffff0000, v74
	v_mul_f32_e32 v74, v74, v74
	v_fmac_f32_e32 v74, v73, v73
	v_add_f32_e32 v72, v72, v74
	v_and_b32_e32 v74, 0xffff0000, v75
	v_lshlrev_b32_e32 v73, 16, v75
	v_mul_f32_e32 v74, v74, v74
	v_fmac_f32_e32 v74, v73, v73
	v_add_f32_e32 v82, v72, v74
	v_lshlrev_b32_e32 v72, 16, v96
	v_and_b32_e32 v73, 0xffff0000, v96
	v_lshlrev_b32_e32 v78, 16, v98
	v_lshlrev_b32_e32 v74, 16, v97
	v_and_b32_e32 v75, 0xffff0000, v97
	v_lshlrev_b32_e32 v80, 16, v99
	v_and_b32_e32 v81, 0xffff0000, v99
	v_pk_add_f32 v[68:69], v[68:69], v[72:73]
	v_pk_add_f32 v[64:65], v[64:65], v[78:79]
	v_pk_add_f32 v[70:71], v[70:71], v[74:75]
	v_pk_add_f32 v[72:73], v[66:67], v[80:81]
	v_cvt_pk_bf16_f32 v66, v68, v69
	v_cvt_pk_bf16_f32 v67, v70, v71
	v_cvt_pk_bf16_f32 v68, v64, v65
	s_nop 0
	v_and_b32_e32 v65, 0xffff0000, v66
	v_lshlrev_b32_e32 v64, 16, v66
	v_mul_f32_e32 v65, v65, v65
	v_fmac_f32_e32 v65, v64, v64
	v_and_b32_e32 v70, 0xffff0000, v67
	v_add_f32_e32 v64, v82, v65
	v_lshlrev_b32_e32 v65, 16, v67
	v_mul_f32_e32 v70, v70, v70
	v_fmac_f32_e32 v70, v65, v65
	v_add_f32_e32 v64, v64, v70
	v_and_b32_e32 v70, 0xffff0000, v68
	v_lshlrev_b32_e32 v65, 16, v68
	v_mul_f32_e32 v70, v70, v70
	v_fmac_f32_e32 v70, v65, v65
	v_cvt_pk_bf16_f32 v69, v72, v73
	v_add_f32_e32 v64, v64, v70
	v_and_b32_e32 v70, 0xffff0000, v69
	v_lshlrev_b32_e32 v65, 16, v69
	v_mul_f32_e32 v70, v70, v70
	v_fmac_f32_e32 v70, v65, v65
	v_add_f32_e32 v64, v64, v70
	v_mov_b32_e32 v65, v64
	s_nop 1
	v_permlane16_swap_b32_e32 v65, v64
	global_store_dwordx4 v[76:77], v[66:69], off offset:256 nt
	s_waitcnt lgkmcnt(0)
	v_add_f32_e32 v64, v64, v65
	v_mov_b32_e32 v65, v64
	s_nop 1
	v_permlane32_swap_b32_e32 v65, v64
	s_and_saveexec_b64 s[6:7], vcc
	s_cbranch_execz .LBB0_158
	s_waitcnt lgkmcnt(0)
	v_add_f32_e32 v66, v64, v65
	v_lshlrev_b64 v[64:65], 6, v[108:109]
	v_lshl_add_u64 v[64:65], s[48:49], 0, v[64:65]
	v_lshl_add_u64 v[64:65], s[74:75], 2, v[64:65]
	s_lshl_b32 s38, s8, 2
	v_lshl_add_u64 v[64:65], v[64:65], 0, s[38:39]
	flat_store_dword v[64:65], v66 sc0 sc1
.LBB0_158:
	s_or_b64 exec, exec, s[6:7]
	v_add_u32_e32 v80, 0x80, v170
	v_ashrrev_i32_e32 v81, 31, v80
	v_lshlrev_b64 v[86:87], 11, v[80:81]
	s_waitcnt lgkmcnt(0)
	v_lshl_add_u64 v[64:65], v[172:173], 0, v[86:87]
	global_load_dwordx4 v[82:85], v[64:65], off
	global_load_dwordx4 v[72:75], v[64:65], off offset:256
	v_add_u32_e32 v76, 0x90, v170
	v_ashrrev_i32_e32 v77, 31, v76
	v_lshlrev_b64 v[78:79], 11, v[76:77]
	v_lshl_add_u64 v[64:65], v[172:173], 0, v[78:79]
	global_load_dwordx4 v[68:71], v[64:65], off
	s_nop 0
	global_load_dwordx4 v[64:67], v[64:65], off offset:256
	s_waitcnt vmcnt(0)
	v_lshlrev_b32_e32 v88, 16, v82
	v_and_b32_e32 v89, 0xffff0000, v82
	v_lshlrev_b32_e32 v82, 16, v83
	v_and_b32_e32 v83, 0xffff0000, v83
	v_lshlrev_b32_e32 v90, 16, v84
	v_and_b32_e32 v91, 0xffff0000, v84
	v_lshlrev_b32_e32 v84, 16, v85
	v_and_b32_e32 v85, 0xffff0000, v85
	v_pk_add_f32 v[60:61], v[60:61], v[88:89]
	v_pk_add_f32 v[62:63], v[62:63], v[82:83]
	v_pk_add_f32 v[82:83], v[58:59], v[84:85]
	v_pk_add_f32 v[58:59], v[56:57], v[90:91]
	v_cvt_pk_bf16_f32 v56, v60, v61
	v_lshl_add_u64 v[60:61], s[68:69], 0, v[86:87]
	v_lshl_add_u64 v[60:61], v[168:169], 1, v[60:61]
	v_cvt_pk_bf16_f32 v57, v62, v63
	v_cvt_pk_bf16_f32 v58, v58, v59
	v_cvt_pk_bf16_f32 v59, v82, v83
	global_store_dwordx4 v[60:61], v[56:59], off nt
	v_lshlrev_b32_e32 v62, 16, v56
	v_and_b32_e32 v63, 0xffff0000, v74
	v_and_b32_e32 v56, 0xffff0000, v56
	v_mul_f32_e32 v56, v56, v56
	v_fmac_f32_e32 v56, v62, v62
	v_lshlrev_b32_e32 v62, 16, v57
	v_and_b32_e32 v57, 0xffff0000, v57
	v_mul_f32_e32 v57, v57, v57
	v_fmac_f32_e32 v57, v62, v62
	v_add_f32_e32 v56, v56, v57
	v_lshlrev_b32_e32 v57, 16, v58
	v_and_b32_e32 v58, 0xffff0000, v58
	v_mul_f32_e32 v58, v58, v58
	v_fmac_f32_e32 v58, v57, v57
	v_add_f32_e32 v56, v56, v58
	v_and_b32_e32 v58, 0xffff0000, v59
	v_lshlrev_b32_e32 v57, 16, v59
	v_mul_f32_e32 v58, v58, v58
	v_fmac_f32_e32 v58, v57, v57
	v_add_f32_e32 v82, v56, v58
	v_lshlrev_b32_e32 v56, 16, v72
	v_and_b32_e32 v57, 0xffff0000, v72
	v_lshlrev_b32_e32 v58, 16, v73
	v_and_b32_e32 v59, 0xffff0000, v73
	v_lshlrev_b32_e32 v62, 16, v74
	v_lshlrev_b32_e32 v72, 16, v75
	v_and_b32_e32 v73, 0xffff0000, v75
	v_pk_add_f32 v[52:53], v[52:53], v[56:57]
	v_pk_add_f32 v[56:57], v[50:51], v[72:73]
	v_pk_add_f32 v[50:51], v[48:49], v[62:63]
	v_cvt_pk_bf16_f32 v48, v52, v53
	v_pk_add_f32 v[54:55], v[54:55], v[58:59]
	v_lshlrev_b32_e32 v52, 16, v48
	v_cvt_pk_bf16_f32 v49, v54, v55
	v_cvt_pk_bf16_f32 v50, v50, v51
	v_cvt_pk_bf16_f32 v51, v56, v57
	global_store_dwordx4 v[60:61], v[48:51], off offset:256 nt
	s_nop 1
	v_and_b32_e32 v48, 0xffff0000, v48
	v_mul_f32_e32 v48, v48, v48
	v_fmac_f32_e32 v48, v52, v52
	v_lshlrev_b32_e32 v52, 16, v49
	v_and_b32_e32 v49, 0xffff0000, v49
	v_mul_f32_e32 v49, v49, v49
	v_add_f32_e32 v48, v82, v48
	v_fmac_f32_e32 v49, v52, v52
	v_add_f32_e32 v48, v48, v49
	v_lshlrev_b32_e32 v49, 16, v50
	v_and_b32_e32 v50, 0xffff0000, v50
	v_mul_f32_e32 v50, v50, v50
	v_fmac_f32_e32 v50, v49, v49
	v_add_f32_e32 v48, v48, v50
	v_and_b32_e32 v50, 0xffff0000, v51
	v_lshlrev_b32_e32 v49, 16, v51
	v_mul_f32_e32 v50, v50, v50
	v_fmac_f32_e32 v50, v49, v49
	v_add_f32_e32 v48, v48, v50
	v_mov_b32_e32 v49, v48
	s_nop 1
	v_permlane16_swap_b32_e32 v49, v48
	s_waitcnt lgkmcnt(0)
	v_add_f32_e32 v48, v48, v49
	v_mov_b32_e32 v49, v48
	s_nop 1
	v_permlane32_swap_b32_e32 v49, v48
	s_and_saveexec_b64 s[6:7], vcc
	s_cbranch_execz .LBB0_160
	s_waitcnt lgkmcnt(0)
	v_add_f32_e32 v50, v48, v49
	v_lshlrev_b64 v[48:49], 6, v[80:81]
	v_lshl_add_u64 v[48:49], s[48:49], 0, v[48:49]
	v_lshl_add_u64 v[48:49], s[74:75], 2, v[48:49]
	s_lshl_b32 s38, s8, 2
	v_lshl_add_u64 v[48:49], v[48:49], 0, s[38:39]
	flat_store_dword v[48:49], v50 sc0 sc1
.LBB0_160:
	s_or_b64 exec, exec, s[6:7]
	v_lshlrev_b32_e32 v48, 16, v68
	s_waitcnt lgkmcnt(0)
	v_and_b32_e32 v49, 0xffff0000, v68
	v_lshlrev_b32_e32 v52, 16, v70
	v_and_b32_e32 v53, 0xffff0000, v70
	v_lshlrev_b32_e32 v54, 16, v71
	v_and_b32_e32 v55, 0xffff0000, v71
	v_pk_add_f32 v[44:45], v[44:45], v[48:49]
	v_lshlrev_b32_e32 v50, 16, v69
	v_and_b32_e32 v51, 0xffff0000, v69
	v_pk_add_f32 v[48:49], v[42:43], v[54:55]
	v_pk_add_f32 v[42:43], v[40:41], v[52:53]
	v_cvt_pk_bf16_f32 v40, v44, v45
	v_lshl_add_u64 v[44:45], s[68:69], 0, v[78:79]
	v_pk_add_f32 v[46:47], v[46:47], v[50:51]
	v_lshl_add_u64 v[44:45], v[168:169], 1, v[44:45]
	v_cvt_pk_bf16_f32 v41, v46, v47
	v_cvt_pk_bf16_f32 v42, v42, v43
	v_cvt_pk_bf16_f32 v43, v48, v49
	global_store_dwordx4 v[44:45], v[40:43], off nt
	v_lshlrev_b32_e32 v46, 16, v40
	v_and_b32_e32 v47, 0xffff0000, v66
	v_and_b32_e32 v40, 0xffff0000, v40
	v_mul_f32_e32 v40, v40, v40
	v_fmac_f32_e32 v40, v46, v46
	v_lshlrev_b32_e32 v46, 16, v41
	v_and_b32_e32 v41, 0xffff0000, v41
	v_mul_f32_e32 v41, v41, v41
	v_fmac_f32_e32 v41, v46, v46
	v_add_f32_e32 v40, v40, v41
	v_lshlrev_b32_e32 v41, 16, v42
	v_and_b32_e32 v42, 0xffff0000, v42
	v_mul_f32_e32 v42, v42, v42
	v_fmac_f32_e32 v42, v41, v41
	v_add_f32_e32 v40, v40, v42
	v_and_b32_e32 v42, 0xffff0000, v43
	v_lshlrev_b32_e32 v41, 16, v43
	v_mul_f32_e32 v42, v42, v42
	v_fmac_f32_e32 v42, v41, v41
	v_add_f32_e32 v50, v40, v42
	v_lshlrev_b32_e32 v40, 16, v64
	v_and_b32_e32 v41, 0xffff0000, v64
	v_lshlrev_b32_e32 v46, 16, v66
	v_lshlrev_b32_e32 v42, 16, v65
	v_and_b32_e32 v43, 0xffff0000, v65
	v_lshlrev_b32_e32 v48, 16, v67
	v_and_b32_e32 v49, 0xffff0000, v67
	v_pk_add_f32 v[36:37], v[36:37], v[40:41]
	v_pk_add_f32 v[32:33], v[32:33], v[46:47]
	v_pk_add_f32 v[38:39], v[38:39], v[42:43]
	v_pk_add_f32 v[40:41], v[34:35], v[48:49]
	v_cvt_pk_bf16_f32 v34, v36, v37
	v_cvt_pk_bf16_f32 v35, v38, v39
	v_cvt_pk_bf16_f32 v36, v32, v33
	s_nop 0
	v_and_b32_e32 v33, 0xffff0000, v34
	v_lshlrev_b32_e32 v32, 16, v34
	v_mul_f32_e32 v33, v33, v33
	v_fmac_f32_e32 v33, v32, v32
	v_and_b32_e32 v38, 0xffff0000, v35
	v_add_f32_e32 v32, v50, v33
	v_lshlrev_b32_e32 v33, 16, v35
	v_mul_f32_e32 v38, v38, v38
	v_fmac_f32_e32 v38, v33, v33
	v_add_f32_e32 v32, v32, v38
	v_and_b32_e32 v38, 0xffff0000, v36
	v_lshlrev_b32_e32 v33, 16, v36
	v_mul_f32_e32 v38, v38, v38
	v_fmac_f32_e32 v38, v33, v33
	v_cvt_pk_bf16_f32 v37, v40, v41
	v_add_f32_e32 v32, v32, v38
	v_and_b32_e32 v38, 0xffff0000, v37
	v_lshlrev_b32_e32 v33, 16, v37
	v_mul_f32_e32 v38, v38, v38
	v_fmac_f32_e32 v38, v33, v33
	v_add_f32_e32 v32, v32, v38
	v_mov_b32_e32 v33, v32
	s_nop 1
	v_permlane16_swap_b32_e32 v33, v32
	global_store_dwordx4 v[44:45], v[34:37], off offset:256 nt
	s_waitcnt lgkmcnt(0)
	v_add_f32_e32 v32, v32, v33
	v_mov_b32_e32 v33, v32
	s_nop 1
	v_permlane32_swap_b32_e32 v33, v32
	s_and_saveexec_b64 s[6:7], vcc
	s_cbranch_execz .LBB0_162
	s_waitcnt lgkmcnt(0)
	v_add_f32_e32 v34, v32, v33
	v_lshlrev_b64 v[32:33], 6, v[76:77]
	v_lshl_add_u64 v[32:33], s[48:49], 0, v[32:33]
	v_lshl_add_u64 v[32:33], s[74:75], 2, v[32:33]
	s_lshl_b32 s38, s8, 2
	v_lshl_add_u64 v[32:33], v[32:33], 0, s[38:39]
	flat_store_dword v[32:33], v34 sc0 sc1
.LBB0_162:
	s_or_b64 exec, exec, s[6:7]
	v_add_u32_e32 v48, 0xa0, v170
	v_ashrrev_i32_e32 v49, 31, v48
	v_lshlrev_b64 v[54:55], 11, v[48:49]
	s_waitcnt lgkmcnt(0)
	v_lshl_add_u64 v[32:33], v[172:173], 0, v[54:55]
	global_load_dwordx4 v[50:53], v[32:33], off
	global_load_dwordx4 v[40:43], v[32:33], off offset:256
	v_add_u32_e32 v44, 0xb0, v170
	v_ashrrev_i32_e32 v45, 31, v44
	v_lshlrev_b64 v[46:47], 11, v[44:45]
	v_lshl_add_u64 v[32:33], v[172:173], 0, v[46:47]
	global_load_dwordx4 v[36:39], v[32:33], off
	s_nop 0
	global_load_dwordx4 v[32:35], v[32:33], off offset:256
	s_waitcnt vmcnt(0)
	v_lshlrev_b32_e32 v56, 16, v50
	v_and_b32_e32 v57, 0xffff0000, v50
	v_lshlrev_b32_e32 v50, 16, v51
	v_and_b32_e32 v51, 0xffff0000, v51
	v_lshlrev_b32_e32 v58, 16, v52
	v_and_b32_e32 v59, 0xffff0000, v52
	v_lshlrev_b32_e32 v52, 16, v53
	v_and_b32_e32 v53, 0xffff0000, v53
	v_pk_add_f32 v[28:29], v[28:29], v[56:57]
	v_pk_add_f32 v[30:31], v[30:31], v[50:51]
	v_pk_add_f32 v[50:51], v[26:27], v[52:53]
	v_pk_add_f32 v[26:27], v[24:25], v[58:59]
	v_cvt_pk_bf16_f32 v24, v28, v29
	v_lshl_add_u64 v[28:29], s[68:69], 0, v[54:55]
	v_lshl_add_u64 v[28:29], v[168:169], 1, v[28:29]
	v_cvt_pk_bf16_f32 v25, v30, v31
	v_cvt_pk_bf16_f32 v26, v26, v27
	v_cvt_pk_bf16_f32 v27, v50, v51
	global_store_dwordx4 v[28:29], v[24:27], off nt
	v_lshlrev_b32_e32 v30, 16, v24
	v_and_b32_e32 v31, 0xffff0000, v42
	v_and_b32_e32 v24, 0xffff0000, v24
	v_mul_f32_e32 v24, v24, v24
	v_fmac_f32_e32 v24, v30, v30
	v_lshlrev_b32_e32 v30, 16, v25
	v_and_b32_e32 v25, 0xffff0000, v25
	v_mul_f32_e32 v25, v25, v25
	v_fmac_f32_e32 v25, v30, v30
	v_add_f32_e32 v24, v24, v25
	v_lshlrev_b32_e32 v25, 16, v26
	v_and_b32_e32 v26, 0xffff0000, v26
	v_mul_f32_e32 v26, v26, v26
	v_fmac_f32_e32 v26, v25, v25
	v_add_f32_e32 v24, v24, v26
	v_and_b32_e32 v26, 0xffff0000, v27
	v_lshlrev_b32_e32 v25, 16, v27
	v_mul_f32_e32 v26, v26, v26
	v_fmac_f32_e32 v26, v25, v25
	v_add_f32_e32 v50, v24, v26
	v_lshlrev_b32_e32 v24, 16, v40
	v_and_b32_e32 v25, 0xffff0000, v40
	v_lshlrev_b32_e32 v26, 16, v41
	v_and_b32_e32 v27, 0xffff0000, v41
	v_lshlrev_b32_e32 v30, 16, v42
	v_lshlrev_b32_e32 v40, 16, v43
	v_and_b32_e32 v41, 0xffff0000, v43
	v_pk_add_f32 v[20:21], v[20:21], v[24:25]
	v_pk_add_f32 v[24:25], v[18:19], v[40:41]
	v_pk_add_f32 v[18:19], v[16:17], v[30:31]
	v_cvt_pk_bf16_f32 v16, v20, v21
	v_pk_add_f32 v[22:23], v[22:23], v[26:27]
	v_lshlrev_b32_e32 v20, 16, v16
	v_cvt_pk_bf16_f32 v17, v22, v23
	v_cvt_pk_bf16_f32 v18, v18, v19
	v_cvt_pk_bf16_f32 v19, v24, v25
	global_store_dwordx4 v[28:29], v[16:19], off offset:256 nt
	s_nop 1
	v_and_b32_e32 v16, 0xffff0000, v16
	v_mul_f32_e32 v16, v16, v16
	v_fmac_f32_e32 v16, v20, v20
	v_lshlrev_b32_e32 v20, 16, v17
	v_and_b32_e32 v17, 0xffff0000, v17
	v_mul_f32_e32 v17, v17, v17
	v_add_f32_e32 v16, v50, v16
	v_fmac_f32_e32 v17, v20, v20
	v_add_f32_e32 v16, v16, v17
	v_lshlrev_b32_e32 v17, 16, v18
	v_and_b32_e32 v18, 0xffff0000, v18
	v_mul_f32_e32 v18, v18, v18
	v_fmac_f32_e32 v18, v17, v17
	v_add_f32_e32 v16, v16, v18
	v_and_b32_e32 v18, 0xffff0000, v19
	v_lshlrev_b32_e32 v17, 16, v19
	v_mul_f32_e32 v18, v18, v18
	v_fmac_f32_e32 v18, v17, v17
	v_add_f32_e32 v16, v16, v18
	v_mov_b32_e32 v17, v16
	s_nop 1
	v_permlane16_swap_b32_e32 v17, v16
	s_waitcnt lgkmcnt(0)
	v_add_f32_e32 v16, v16, v17
	v_mov_b32_e32 v17, v16
	s_nop 1
	v_permlane32_swap_b32_e32 v17, v16
	s_and_saveexec_b64 s[6:7], vcc
	s_cbranch_execz .LBB0_164
	s_waitcnt lgkmcnt(0)
	v_add_f32_e32 v18, v16, v17
	v_lshlrev_b64 v[16:17], 6, v[48:49]
	v_lshl_add_u64 v[16:17], s[48:49], 0, v[16:17]
	v_lshl_add_u64 v[16:17], s[74:75], 2, v[16:17]
	s_lshl_b32 s38, s8, 2
	v_lshl_add_u64 v[16:17], v[16:17], 0, s[38:39]
	flat_store_dword v[16:17], v18 sc0 sc1
.LBB0_164:
	s_or_b64 exec, exec, s[6:7]
	v_lshlrev_b32_e32 v16, 16, v36
	s_waitcnt lgkmcnt(0)
	v_and_b32_e32 v17, 0xffff0000, v36
	v_lshlrev_b32_e32 v20, 16, v38
	v_and_b32_e32 v21, 0xffff0000, v38
	v_lshlrev_b32_e32 v22, 16, v39
	v_and_b32_e32 v23, 0xffff0000, v39
	v_pk_add_f32 v[12:13], v[12:13], v[16:17]
	v_lshlrev_b32_e32 v18, 16, v37
	v_and_b32_e32 v19, 0xffff0000, v37
	v_pk_add_f32 v[16:17], v[10:11], v[22:23]
	v_pk_add_f32 v[10:11], v[8:9], v[20:21]
	v_cvt_pk_bf16_f32 v8, v12, v13
	v_lshl_add_u64 v[12:13], s[68:69], 0, v[46:47]
	v_pk_add_f32 v[14:15], v[14:15], v[18:19]
	v_lshl_add_u64 v[12:13], v[168:169], 1, v[12:13]
	v_cvt_pk_bf16_f32 v9, v14, v15
	v_cvt_pk_bf16_f32 v10, v10, v11
	v_cvt_pk_bf16_f32 v11, v16, v17
	global_store_dwordx4 v[12:13], v[8:11], off nt
	v_lshlrev_b32_e32 v14, 16, v8
	v_and_b32_e32 v15, 0xffff0000, v34
	v_and_b32_e32 v8, 0xffff0000, v8
	v_mul_f32_e32 v8, v8, v8
	v_fmac_f32_e32 v8, v14, v14
	v_lshlrev_b32_e32 v14, 16, v9
	v_and_b32_e32 v9, 0xffff0000, v9
	v_mul_f32_e32 v9, v9, v9
	v_fmac_f32_e32 v9, v14, v14
	v_add_f32_e32 v8, v8, v9
	v_lshlrev_b32_e32 v9, 16, v10
	v_and_b32_e32 v10, 0xffff0000, v10
	v_mul_f32_e32 v10, v10, v10
	v_fmac_f32_e32 v10, v9, v9
	v_add_f32_e32 v8, v8, v10
	v_and_b32_e32 v10, 0xffff0000, v11
	v_lshlrev_b32_e32 v9, 16, v11
	v_mul_f32_e32 v10, v10, v10
	v_fmac_f32_e32 v10, v9, v9
	v_add_f32_e32 v18, v8, v10
	v_lshlrev_b32_e32 v8, 16, v32
	v_and_b32_e32 v9, 0xffff0000, v32
	v_lshlrev_b32_e32 v14, 16, v34
	v_lshlrev_b32_e32 v10, 16, v33
	v_and_b32_e32 v11, 0xffff0000, v33
	v_lshlrev_b32_e32 v16, 16, v35
	v_and_b32_e32 v17, 0xffff0000, v35
	v_pk_add_f32 v[4:5], v[4:5], v[8:9]
	v_pk_add_f32 v[0:1], v[0:1], v[14:15]
	v_pk_add_f32 v[6:7], v[6:7], v[10:11]
	v_pk_add_f32 v[8:9], v[2:3], v[16:17]
	v_cvt_pk_bf16_f32 v2, v4, v5
	v_cvt_pk_bf16_f32 v3, v6, v7
	v_cvt_pk_bf16_f32 v4, v0, v1
	s_nop 0
	v_and_b32_e32 v1, 0xffff0000, v2
	v_lshlrev_b32_e32 v0, 16, v2
	v_mul_f32_e32 v1, v1, v1
	v_fmac_f32_e32 v1, v0, v0
	v_and_b32_e32 v6, 0xffff0000, v3
	v_add_f32_e32 v0, v18, v1
	v_lshlrev_b32_e32 v1, 16, v3
	v_mul_f32_e32 v6, v6, v6
	v_fmac_f32_e32 v6, v1, v1
	v_add_f32_e32 v0, v0, v6
	v_and_b32_e32 v6, 0xffff0000, v4
	v_lshlrev_b32_e32 v1, 16, v4
	v_mul_f32_e32 v6, v6, v6
	v_fmac_f32_e32 v6, v1, v1
	v_cvt_pk_bf16_f32 v5, v8, v9
	v_add_f32_e32 v0, v0, v6
	v_and_b32_e32 v6, 0xffff0000, v5
	v_lshlrev_b32_e32 v1, 16, v5
	v_mul_f32_e32 v6, v6, v6
	v_fmac_f32_e32 v6, v1, v1
	v_add_f32_e32 v0, v0, v6
	v_mov_b32_e32 v1, v0
	s_nop 1
	v_permlane16_swap_b32_e32 v1, v0
	global_store_dwordx4 v[12:13], v[2:5], off offset:256 nt
	s_waitcnt lgkmcnt(0)
	v_add_f32_e32 v0, v0, v1
	v_mov_b32_e32 v1, v0
	s_nop 1
	v_permlane32_swap_b32_e32 v1, v0
	s_and_saveexec_b64 s[6:7], vcc
	s_cbranch_execz .LBB0_166
	s_waitcnt lgkmcnt(0)
	v_add_f32_e32 v2, v0, v1
	v_lshlrev_b64 v[0:1], 6, v[44:45]
	v_lshl_add_u64 v[0:1], s[48:49], 0, v[0:1]
	v_lshl_add_u64 v[0:1], s[74:75], 2, v[0:1]
	s_lshl_b32 s38, s8, 2
	v_lshl_add_u64 v[0:1], v[0:1], 0, s[38:39]
	flat_store_dword v[0:1], v2 sc0 sc1

.LBB0_336:
	s_mov_b32 s6, -1
	s_lshl_b32 s5, s5, 8
	v_mbcnt_lo_u32_b32 v128, s6, 0
	v_mbcnt_hi_u32_b32 v128, s6, v128
	s_getreg_b32 s6, hwreg(HW_REG_HW_ID, 0, 6)
	s_and_b32 s6, s6, 63
	s_lshl_b32 s6, s6, 2
	s_add_i32 s6, s6, 0
	s_add_i32 s6, s6, 0x20200
	v_mov_b32_e32 v129, s6
	ds_read_b32 v129, v129
	v_bfrev_b32_e32 v130, 0.5
	s_lshl_b32 s56, s4, 2
	s_ashr_i32 s57, s56, 31
	s_waitcnt lgkmcnt(0)
	v_readfirstlane_b32 s6, v129
	s_nop 1
	v_lshl_add_u32 v128, s6, 6, v128
	s_nop 0
	v_readfirstlane_b32 s6, v128
	s_bfe_u32 s8, s6, 0x20006
	s_ashr_i32 s6, s6, 2
	s_andn2_b32 s6, s6, 63
	s_add_i32 s6, s6, s5
	v_and_or_b32 v170, v128, 15, s6
	s_lshl_b32 s5, s4, 8
	s_lshl_b32 s6, s8, 5
	v_bfe_u32 v129, v128, 4, 2
	s_or_b32 s5, s6, s5
	v_lshl_or_b32 v168, v129, 3, s5
	v_ashrrev_i32_e32 v169, 31, v168
	v_lshlrev_b64 v[146:147], 1, v[168:169]
	v_ashrrev_i32_e32 v171, 31, v170
	v_lshlrev_b32_e32 v128, 2, v128
	v_lshl_add_u64 v[172:173], s[68:69], 0, v[146:147]
	v_lshlrev_b64 v[148:149], 11, v[170:171]
	v_bitop3_b32 v181, v128, 64, v130 bitop3:0x6c
	v_bitop3_b32 v180, v128, s84, v130 bitop3:0x6c
	v_cmp_eq_u32_e32 vcc, 0, v129
	v_lshl_add_u64 v[128:129], v[172:173], 0, v[148:149]
	global_load_dwordx4 v[142:145], v[128:129], off
	global_load_dwordx4 v[136:139], v[128:129], off offset:256
	v_or_b32_e32 v174, 16, v170
	v_ashrrev_i32_e32 v175, 31, v174
	v_lshlrev_b64 v[176:177], 11, v[174:175]
	v_lshl_add_u64 v[128:129], v[172:173], 0, v[176:177]
	global_load_dwordx4 v[132:135], v[128:129], off
	s_nop 0
	global_load_dwordx4 v[128:131], v[128:129], off offset:256
	s_waitcnt vmcnt(0)
	v_lshlrev_b32_e32 v150, 16, v142
	v_and_b32_e32 v151, 0xffff0000, v142
	v_lshlrev_b32_e32 v142, 16, v143
	v_and_b32_e32 v143, 0xffff0000, v143
	v_lshlrev_b32_e32 v152, 16, v144
	v_and_b32_e32 v153, 0xffff0000, v144
	v_lshlrev_b32_e32 v144, 16, v145
	v_and_b32_e32 v145, 0xffff0000, v145
	v_pk_add_f32 v[124:125], v[124:125], v[150:151]
	v_pk_add_f32 v[126:127], v[126:127], v[142:143]
	v_pk_add_f32 v[142:143], v[122:123], v[144:145]
	v_pk_add_f32 v[122:123], v[120:121], v[152:153]
	v_cvt_pk_bf16_f32 v120, v124, v125
	v_lshl_add_u64 v[124:125], s[68:69], 0, v[148:149]
	v_lshl_add_u64 v[124:125], v[124:125], 0, v[146:147]
	v_cvt_pk_bf16_f32 v121, v126, v127
	v_cvt_pk_bf16_f32 v122, v122, v123
	v_cvt_pk_bf16_f32 v123, v142, v143
	global_store_dwordx4 v[124:125], v[120:123], off nt
	v_lshlrev_b32_e32 v126, 16, v120
	v_and_b32_e32 v127, 0xffff0000, v138
	v_and_b32_e32 v120, 0xffff0000, v120
	v_mul_f32_e32 v120, v120, v120
	v_fmac_f32_e32 v120, v126, v126
	v_lshlrev_b32_e32 v126, 16, v121
	v_and_b32_e32 v121, 0xffff0000, v121
	v_mul_f32_e32 v121, v121, v121
	v_fmac_f32_e32 v121, v126, v126
	v_add_f32_e32 v120, v120, v121
	v_lshlrev_b32_e32 v121, 16, v122
	v_and_b32_e32 v122, 0xffff0000, v122
	v_mul_f32_e32 v122, v122, v122
	v_fmac_f32_e32 v122, v121, v121
	v_add_f32_e32 v120, v120, v122
	v_and_b32_e32 v122, 0xffff0000, v123
	v_lshlrev_b32_e32 v121, 16, v123
	v_mul_f32_e32 v122, v122, v122
	v_fmac_f32_e32 v122, v121, v121
	v_add_f32_e32 v142, v120, v122
	v_lshlrev_b32_e32 v120, 16, v136
	v_and_b32_e32 v121, 0xffff0000, v136
	v_lshlrev_b32_e32 v122, 16, v137
	v_and_b32_e32 v123, 0xffff0000, v137
	v_lshlrev_b32_e32 v126, 16, v138
	v_lshlrev_b32_e32 v136, 16, v139
	v_and_b32_e32 v137, 0xffff0000, v139
	v_pk_add_f32 v[116:117], v[116:117], v[120:121]
	v_pk_add_f32 v[120:121], v[114:115], v[136:137]
	v_pk_add_f32 v[114:115], v[112:113], v[126:127]
	v_cvt_pk_bf16_f32 v112, v116, v117
	v_pk_add_f32 v[118:119], v[118:119], v[122:123]
	v_lshlrev_b32_e32 v116, 16, v112
	v_cvt_pk_bf16_f32 v113, v118, v119
	v_cvt_pk_bf16_f32 v114, v114, v115
	v_cvt_pk_bf16_f32 v115, v120, v121
	global_store_dwordx4 v[124:125], v[112:115], off offset:256 nt
	s_nop 1
	v_and_b32_e32 v112, 0xffff0000, v112
	v_mul_f32_e32 v112, v112, v112
	v_fmac_f32_e32 v112, v116, v116
	v_lshlrev_b32_e32 v116, 16, v113
	v_and_b32_e32 v113, 0xffff0000, v113
	v_mul_f32_e32 v113, v113, v113
	v_add_f32_e32 v112, v142, v112
	v_fmac_f32_e32 v113, v116, v116
	v_add_f32_e32 v112, v112, v113
	v_lshlrev_b32_e32 v113, 16, v114
	v_and_b32_e32 v114, 0xffff0000, v114
	v_mul_f32_e32 v114, v114, v114
	v_fmac_f32_e32 v114, v113, v113
	v_add_f32_e32 v112, v112, v114
	v_and_b32_e32 v114, 0xffff0000, v115
	v_lshlrev_b32_e32 v113, 16, v115
	v_mul_f32_e32 v114, v114, v114
	v_fmac_f32_e32 v114, v113, v113
	v_add_f32_e32 v112, v112, v114
	v_mov_b32_e32 v113, v112
	s_nop 1
	v_permlane16_swap_b32_e32 v113, v112
	s_waitcnt lgkmcnt(0)
	v_add_f32_e32 v112, v112, v113
	v_mov_b32_e32 v113, v112
	s_nop 1
	v_permlane32_swap_b32_e32 v113, v112
	s_and_saveexec_b64 s[6:7], vcc
	s_cbranch_execz .LBB0_338
	s_waitcnt lgkmcnt(0)
	v_add_f32_e32 v114, v112, v113
	v_lshlrev_b64 v[112:113], 6, v[170:171]
	v_lshl_add_u64 v[112:113], s[46:47], 0, v[112:113]
	v_lshl_add_u64 v[112:113], s[56:57], 2, v[112:113]
	s_lshl_b32 s38, s8, 2
	v_lshl_add_u64 v[112:113], v[112:113], 0, s[38:39]
	flat_store_dword v[112:113], v114 sc0 sc1
.LBB0_338:
	s_or_b64 exec, exec, s[6:7]
	v_lshlrev_b32_e32 v112, 16, v132
	s_waitcnt lgkmcnt(0)
	v_and_b32_e32 v113, 0xffff0000, v132
	v_lshlrev_b32_e32 v116, 16, v134
	v_and_b32_e32 v117, 0xffff0000, v134
	v_lshlrev_b32_e32 v118, 16, v135
	v_and_b32_e32 v119, 0xffff0000, v135
	v_pk_add_f32 v[108:109], v[108:109], v[112:113]
	v_lshlrev_b32_e32 v114, 16, v133
	v_and_b32_e32 v115, 0xffff0000, v133
	v_pk_add_f32 v[112:113], v[106:107], v[118:119]
	v_pk_add_f32 v[106:107], v[104:105], v[116:117]
	v_cvt_pk_bf16_f32 v104, v108, v109
	v_lshl_add_u64 v[108:109], s[68:69], 0, v[176:177]
	v_pk_add_f32 v[110:111], v[110:111], v[114:115]
	v_lshl_add_u64 v[108:109], v[168:169], 1, v[108:109]
	v_cvt_pk_bf16_f32 v105, v110, v111
	v_cvt_pk_bf16_f32 v106, v106, v107
	v_cvt_pk_bf16_f32 v107, v112, v113
	global_store_dwordx4 v[108:109], v[104:107], off nt
	v_lshlrev_b32_e32 v110, 16, v104
	v_and_b32_e32 v111, 0xffff0000, v130
	v_and_b32_e32 v104, 0xffff0000, v104
	v_mul_f32_e32 v104, v104, v104
	v_fmac_f32_e32 v104, v110, v110
	v_lshlrev_b32_e32 v110, 16, v105
	v_and_b32_e32 v105, 0xffff0000, v105
	v_mul_f32_e32 v105, v105, v105
	v_fmac_f32_e32 v105, v110, v110
	v_add_f32_e32 v104, v104, v105
	v_lshlrev_b32_e32 v105, 16, v106
	v_and_b32_e32 v106, 0xffff0000, v106
	v_mul_f32_e32 v106, v106, v106
	v_fmac_f32_e32 v106, v105, v105
	v_add_f32_e32 v104, v104, v106
	v_and_b32_e32 v106, 0xffff0000, v107
	v_lshlrev_b32_e32 v105, 16, v107
	v_mul_f32_e32 v106, v106, v106
	v_fmac_f32_e32 v106, v105, v105
	v_add_f32_e32 v114, v104, v106
	v_lshlrev_b32_e32 v104, 16, v128
	v_and_b32_e32 v105, 0xffff0000, v128
	v_lshlrev_b32_e32 v110, 16, v130
	v_lshlrev_b32_e32 v106, 16, v129
	v_and_b32_e32 v107, 0xffff0000, v129
	v_lshlrev_b32_e32 v112, 16, v131
	v_and_b32_e32 v113, 0xffff0000, v131
	v_pk_add_f32 v[100:101], v[100:101], v[104:105]
	v_pk_add_f32 v[96:97], v[96:97], v[110:111]
	v_pk_add_f32 v[102:103], v[102:103], v[106:107]
	v_pk_add_f32 v[104:105], v[98:99], v[112:113]
	v_cvt_pk_bf16_f32 v98, v100, v101
	v_cvt_pk_bf16_f32 v99, v102, v103
	v_cvt_pk_bf16_f32 v100, v96, v97
	s_nop 0
	v_and_b32_e32 v97, 0xffff0000, v98
	v_lshlrev_b32_e32 v96, 16, v98
	v_mul_f32_e32 v97, v97, v97
	v_fmac_f32_e32 v97, v96, v96
	v_and_b32_e32 v102, 0xffff0000, v99
	v_add_f32_e32 v96, v114, v97
	v_lshlrev_b32_e32 v97, 16, v99
	v_mul_f32_e32 v102, v102, v102
	v_fmac_f32_e32 v102, v97, v97
	v_add_f32_e32 v96, v96, v102
	v_and_b32_e32 v102, 0xffff0000, v100
	v_lshlrev_b32_e32 v97, 16, v100
	v_mul_f32_e32 v102, v102, v102
	v_fmac_f32_e32 v102, v97, v97
	v_cvt_pk_bf16_f32 v101, v104, v105
	v_add_f32_e32 v96, v96, v102
	v_and_b32_e32 v102, 0xffff0000, v101
	v_lshlrev_b32_e32 v97, 16, v101
	v_mul_f32_e32 v102, v102, v102
	v_fmac_f32_e32 v102, v97, v97
	v_add_f32_e32 v96, v96, v102
	v_mov_b32_e32 v97, v96
	s_nop 1
	v_permlane16_swap_b32_e32 v97, v96
	global_store_dwordx4 v[108:109], v[98:101], off offset:256 nt
	s_waitcnt lgkmcnt(0)
	v_add_f32_e32 v96, v96, v97
	v_mov_b32_e32 v97, v96
	s_nop 1
	v_permlane32_swap_b32_e32 v97, v96
	s_and_saveexec_b64 s[6:7], vcc
	s_cbranch_execz .LBB0_340
	s_waitcnt lgkmcnt(0)
	v_add_f32_e32 v98, v96, v97
	v_lshlrev_b64 v[96:97], 6, v[174:175]
	v_lshl_add_u64 v[96:97], s[46:47], 0, v[96:97]
	v_lshl_add_u64 v[96:97], s[56:57], 2, v[96:97]
	s_lshl_b32 s38, s8, 2
	v_lshl_add_u64 v[96:97], v[96:97], 0, s[38:39]
	flat_store_dword v[96:97], v98 sc0 sc1
.LBB0_340:
	s_or_b64 exec, exec, s[6:7]
	v_or_b32_e32 v112, 32, v170
	v_ashrrev_i32_e32 v113, 31, v112
	v_lshlrev_b64 v[118:119], 11, v[112:113]
	s_waitcnt lgkmcnt(0)
	v_lshl_add_u64 v[96:97], v[172:173], 0, v[118:119]
	global_load_dwordx4 v[114:117], v[96:97], off
	global_load_dwordx4 v[104:107], v[96:97], off offset:256
	v_or_b32_e32 v108, 48, v170
	v_ashrrev_i32_e32 v109, 31, v108
	v_lshlrev_b64 v[110:111], 11, v[108:109]
	v_lshl_add_u64 v[96:97], v[172:173], 0, v[110:111]
	global_load_dwordx4 v[100:103], v[96:97], off
	s_nop 0
	global_load_dwordx4 v[96:99], v[96:97], off offset:256
	s_waitcnt vmcnt(0)
	v_lshlrev_b32_e32 v120, 16, v114
	v_and_b32_e32 v121, 0xffff0000, v114
	v_lshlrev_b32_e32 v114, 16, v115
	v_and_b32_e32 v115, 0xffff0000, v115
	v_lshlrev_b32_e32 v122, 16, v116
	v_and_b32_e32 v123, 0xffff0000, v116
	v_lshlrev_b32_e32 v116, 16, v117
	v_and_b32_e32 v117, 0xffff0000, v117
	v_pk_add_f32 v[92:93], v[92:93], v[120:121]
	v_pk_add_f32 v[94:95], v[94:95], v[114:115]
	v_pk_add_f32 v[114:115], v[90:91], v[116:117]
	v_pk_add_f32 v[90:91], v[88:89], v[122:123]
	v_cvt_pk_bf16_f32 v88, v92, v93
	v_lshl_add_u64 v[92:93], s[68:69], 0, v[118:119]
	v_lshl_add_u64 v[92:93], v[168:169], 1, v[92:93]
	v_cvt_pk_bf16_f32 v89, v94, v95
	v_cvt_pk_bf16_f32 v90, v90, v91
	v_cvt_pk_bf16_f32 v91, v114, v115
	global_store_dwordx4 v[92:93], v[88:91], off nt
	v_lshlrev_b32_e32 v94, 16, v88
	v_and_b32_e32 v95, 0xffff0000, v106
	v_and_b32_e32 v88, 0xffff0000, v88
	v_mul_f32_e32 v88, v88, v88
	v_fmac_f32_e32 v88, v94, v94
	v_lshlrev_b32_e32 v94, 16, v89
	v_and_b32_e32 v89, 0xffff0000, v89
	v_mul_f32_e32 v89, v89, v89
	v_fmac_f32_e32 v89, v94, v94
	v_add_f32_e32 v88, v88, v89
	v_lshlrev_b32_e32 v89, 16, v90
	v_and_b32_e32 v90, 0xffff0000, v90
	v_mul_f32_e32 v90, v90, v90
	v_fmac_f32_e32 v90, v89, v89
	v_add_f32_e32 v88, v88, v90
	v_and_b32_e32 v90, 0xffff0000, v91
	v_lshlrev_b32_e32 v89, 16, v91
	v_mul_f32_e32 v90, v90, v90
	v_fmac_f32_e32 v90, v89, v89
	v_add_f32_e32 v114, v88, v90
	v_lshlrev_b32_e32 v88, 16, v104
	v_and_b32_e32 v89, 0xffff0000, v104
	v_lshlrev_b32_e32 v90, 16, v105
	v_and_b32_e32 v91, 0xffff0000, v105
	v_lshlrev_b32_e32 v94, 16, v106
	v_lshlrev_b32_e32 v104, 16, v107
	v_and_b32_e32 v105, 0xffff0000, v107
	v_pk_add_f32 v[84:85], v[84:85], v[88:89]
	v_pk_add_f32 v[88:89], v[82:83], v[104:105]
	v_pk_add_f32 v[82:83], v[80:81], v[94:95]
	v_cvt_pk_bf16_f32 v80, v84, v85
	v_pk_add_f32 v[86:87], v[86:87], v[90:91]
	v_lshlrev_b32_e32 v84, 16, v80
	v_cvt_pk_bf16_f32 v81, v86, v87
	v_cvt_pk_bf16_f32 v82, v82, v83
	v_cvt_pk_bf16_f32 v83, v88, v89
	global_store_dwordx4 v[92:93], v[80:83], off offset:256 nt
	s_nop 1
	v_and_b32_e32 v80, 0xffff0000, v80
	v_mul_f32_e32 v80, v80, v80
	v_fmac_f32_e32 v80, v84, v84
	v_lshlrev_b32_e32 v84, 16, v81
	v_and_b32_e32 v81, 0xffff0000, v81
	v_mul_f32_e32 v81, v81, v81
	v_add_f32_e32 v80, v114, v80
	v_fmac_f32_e32 v81, v84, v84
	v_add_f32_e32 v80, v80, v81
	v_lshlrev_b32_e32 v81, 16, v82
	v_and_b32_e32 v82, 0xffff0000, v82
	v_mul_f32_e32 v82, v82, v82
	v_fmac_f32_e32 v82, v81, v81
	v_add_f32_e32 v80, v80, v82
	v_and_b32_e32 v82, 0xffff0000, v83
	v_lshlrev_b32_e32 v81, 16, v83
	v_mul_f32_e32 v82, v82, v82
	v_fmac_f32_e32 v82, v81, v81
	v_add_f32_e32 v80, v80, v82
	v_mov_b32_e32 v81, v80
	s_nop 1
	v_permlane16_swap_b32_e32 v81, v80
	s_waitcnt lgkmcnt(0)
	v_add_f32_e32 v80, v80, v81
	v_mov_b32_e32 v81, v80
	s_nop 1
	v_permlane32_swap_b32_e32 v81, v80
	s_mov_b64 s[6:7], exec
	s_and_b64 s[4:5], s[6:7], vcc
	v_mov_b32_e32 v198, v216
	v_mov_b32_e32 v199, v217
	v_mov_b32_e32 v248, v218
	v_mov_b32_e32 v205, v219
	v_mov_b32_e32 v196, v220
	s_mov_b64 exec, s[4:5]
	s_cbranch_execz .LBB0_342
	s_waitcnt lgkmcnt(0)
	v_add_f32_e32 v82, v80, v81
	v_lshlrev_b64 v[80:81], 6, v[112:113]
	v_lshl_add_u64 v[80:81], s[46:47], 0, v[80:81]
	v_lshl_add_u64 v[80:81], s[56:57], 2, v[80:81]
	s_lshl_b32 s38, s8, 2
	v_lshl_add_u64 v[80:81], v[80:81], 0, s[38:39]
	flat_store_dword v[80:81], v82 sc0 sc1
.LBB0_342:
	s_or_b64 exec, exec, s[6:7]
	v_lshlrev_b32_e32 v80, 16, v100
	s_waitcnt lgkmcnt(0)
	v_and_b32_e32 v81, 0xffff0000, v100
	v_lshlrev_b32_e32 v84, 16, v102
	v_and_b32_e32 v85, 0xffff0000, v102
	v_lshlrev_b32_e32 v86, 16, v103
	v_and_b32_e32 v87, 0xffff0000, v103
	v_pk_add_f32 v[76:77], v[76:77], v[80:81]
	v_lshlrev_b32_e32 v82, 16, v101
	v_and_b32_e32 v83, 0xffff0000, v101
	v_pk_add_f32 v[80:81], v[74:75], v[86:87]
	v_pk_add_f32 v[74:75], v[72:73], v[84:85]
	v_cvt_pk_bf16_f32 v72, v76, v77
	v_lshl_add_u64 v[76:77], s[68:69], 0, v[110:111]
	v_pk_add_f32 v[78:79], v[78:79], v[82:83]
	v_lshl_add_u64 v[76:77], v[168:169], 1, v[76:77]
	v_cvt_pk_bf16_f32 v73, v78, v79
	v_cvt_pk_bf16_f32 v74, v74, v75
	v_cvt_pk_bf16_f32 v75, v80, v81
	global_store_dwordx4 v[76:77], v[72:75], off nt
	v_lshlrev_b32_e32 v78, 16, v72
	v_and_b32_e32 v79, 0xffff0000, v98
	v_and_b32_e32 v72, 0xffff0000, v72
	v_mul_f32_e32 v72, v72, v72
	v_fmac_f32_e32 v72, v78, v78
	v_lshlrev_b32_e32 v78, 16, v73
	v_and_b32_e32 v73, 0xffff0000, v73
	v_mul_f32_e32 v73, v73, v73
	v_fmac_f32_e32 v73, v78, v78
	v_add_f32_e32 v72, v72, v73
	v_lshlrev_b32_e32 v73, 16, v74
	v_and_b32_e32 v74, 0xffff0000, v74
	v_mul_f32_e32 v74, v74, v74
	v_fmac_f32_e32 v74, v73, v73
	v_add_f32_e32 v72, v72, v74
	v_and_b32_e32 v74, 0xffff0000, v75
	v_lshlrev_b32_e32 v73, 16, v75
	v_mul_f32_e32 v74, v74, v74
	v_fmac_f32_e32 v74, v73, v73
	v_add_f32_e32 v82, v72, v74
	v_lshlrev_b32_e32 v72, 16, v96
	v_and_b32_e32 v73, 0xffff0000, v96
	v_lshlrev_b32_e32 v78, 16, v98
	v_lshlrev_b32_e32 v74, 16, v97
	v_and_b32_e32 v75, 0xffff0000, v97
	v_lshlrev_b32_e32 v80, 16, v99
	v_and_b32_e32 v81, 0xffff0000, v99
	v_pk_add_f32 v[68:69], v[68:69], v[72:73]
	v_pk_add_f32 v[64:65], v[64:65], v[78:79]
	v_pk_add_f32 v[70:71], v[70:71], v[74:75]
	v_pk_add_f32 v[72:73], v[66:67], v[80:81]
	v_cvt_pk_bf16_f32 v66, v68, v69
	v_cvt_pk_bf16_f32 v67, v70, v71
	v_cvt_pk_bf16_f32 v68, v64, v65
	s_nop 0
	v_and_b32_e32 v65, 0xffff0000, v66
	v_lshlrev_b32_e32 v64, 16, v66
	v_mul_f32_e32 v65, v65, v65
	v_fmac_f32_e32 v65, v64, v64
	v_and_b32_e32 v70, 0xffff0000, v67
	v_add_f32_e32 v64, v82, v65
	v_lshlrev_b32_e32 v65, 16, v67
	v_mul_f32_e32 v70, v70, v70
	v_fmac_f32_e32 v70, v65, v65
	v_add_f32_e32 v64, v64, v70
	v_and_b32_e32 v70, 0xffff0000, v68
	v_lshlrev_b32_e32 v65, 16, v68
	v_mul_f32_e32 v70, v70, v70
	v_fmac_f32_e32 v70, v65, v65
	v_cvt_pk_bf16_f32 v69, v72, v73
	v_add_f32_e32 v64, v64, v70
	v_and_b32_e32 v70, 0xffff0000, v69
	v_lshlrev_b32_e32 v65, 16, v69
	v_mul_f32_e32 v70, v70, v70
	v_fmac_f32_e32 v70, v65, v65
	v_add_f32_e32 v64, v64, v70
	v_mov_b32_e32 v65, v64
	s_nop 1
	v_permlane16_swap_b32_e32 v65, v64
	global_store_dwordx4 v[76:77], v[66:69], off offset:256 nt
	s_waitcnt lgkmcnt(0)
	v_add_f32_e32 v64, v64, v65
	v_mov_b32_e32 v65, v64
	s_nop 1
	v_permlane32_swap_b32_e32 v65, v64
	s_and_saveexec_b64 s[6:7], vcc
	s_cbranch_execz .LBB0_344
	s_waitcnt lgkmcnt(0)
	v_add_f32_e32 v66, v64, v65
	v_lshlrev_b64 v[64:65], 6, v[108:109]
	v_lshl_add_u64 v[64:65], s[46:47], 0, v[64:65]
	v_lshl_add_u64 v[64:65], s[56:57], 2, v[64:65]
	s_lshl_b32 s38, s8, 2
	v_lshl_add_u64 v[64:65], v[64:65], 0, s[38:39]
	flat_store_dword v[64:65], v66 sc0 sc1
.LBB0_344:
	s_or_b64 exec, exec, s[6:7]
	v_add_u32_e32 v80, 0x80, v170
	v_ashrrev_i32_e32 v81, 31, v80
	v_lshlrev_b64 v[86:87], 11, v[80:81]
	s_waitcnt lgkmcnt(0)
	v_lshl_add_u64 v[64:65], v[172:173], 0, v[86:87]
	global_load_dwordx4 v[82:85], v[64:65], off
	global_load_dwordx4 v[72:75], v[64:65], off offset:256
	v_add_u32_e32 v76, 0x90, v170
	v_ashrrev_i32_e32 v77, 31, v76
	v_lshlrev_b64 v[78:79], 11, v[76:77]
	v_lshl_add_u64 v[64:65], v[172:173], 0, v[78:79]
	global_load_dwordx4 v[68:71], v[64:65], off
	s_nop 0
	global_load_dwordx4 v[64:67], v[64:65], off offset:256
	s_waitcnt vmcnt(0)
	v_lshlrev_b32_e32 v88, 16, v82
	v_and_b32_e32 v89, 0xffff0000, v82
	v_lshlrev_b32_e32 v82, 16, v83
	v_and_b32_e32 v83, 0xffff0000, v83
	v_lshlrev_b32_e32 v90, 16, v84
	v_and_b32_e32 v91, 0xffff0000, v84
	v_lshlrev_b32_e32 v84, 16, v85
	v_and_b32_e32 v85, 0xffff0000, v85
	v_pk_add_f32 v[60:61], v[60:61], v[88:89]
	v_pk_add_f32 v[62:63], v[62:63], v[82:83]
	v_pk_add_f32 v[82:83], v[58:59], v[84:85]
	v_pk_add_f32 v[58:59], v[56:57], v[90:91]
	v_cvt_pk_bf16_f32 v56, v60, v61
	v_lshl_add_u64 v[60:61], s[68:69], 0, v[86:87]
	v_lshl_add_u64 v[60:61], v[168:169], 1, v[60:61]
	v_cvt_pk_bf16_f32 v57, v62, v63
	v_cvt_pk_bf16_f32 v58, v58, v59
	v_cvt_pk_bf16_f32 v59, v82, v83
	global_store_dwordx4 v[60:61], v[56:59], off nt
	v_lshlrev_b32_e32 v62, 16, v56
	v_and_b32_e32 v63, 0xffff0000, v74
	v_and_b32_e32 v56, 0xffff0000, v56
	v_mul_f32_e32 v56, v56, v56
	v_fmac_f32_e32 v56, v62, v62
	v_lshlrev_b32_e32 v62, 16, v57
	v_and_b32_e32 v57, 0xffff0000, v57
	v_mul_f32_e32 v57, v57, v57
	v_fmac_f32_e32 v57, v62, v62
	v_add_f32_e32 v56, v56, v57
	v_lshlrev_b32_e32 v57, 16, v58
	v_and_b32_e32 v58, 0xffff0000, v58
	v_mul_f32_e32 v58, v58, v58
	v_fmac_f32_e32 v58, v57, v57
	v_add_f32_e32 v56, v56, v58
	v_and_b32_e32 v58, 0xffff0000, v59
	v_lshlrev_b32_e32 v57, 16, v59
	v_mul_f32_e32 v58, v58, v58
	v_fmac_f32_e32 v58, v57, v57
	v_add_f32_e32 v82, v56, v58
	v_lshlrev_b32_e32 v56, 16, v72
	v_and_b32_e32 v57, 0xffff0000, v72
	v_lshlrev_b32_e32 v58, 16, v73
	v_and_b32_e32 v59, 0xffff0000, v73
	v_lshlrev_b32_e32 v62, 16, v74
	v_lshlrev_b32_e32 v72, 16, v75
	v_and_b32_e32 v73, 0xffff0000, v75
	v_pk_add_f32 v[52:53], v[52:53], v[56:57]
	v_pk_add_f32 v[56:57], v[50:51], v[72:73]
	v_pk_add_f32 v[50:51], v[48:49], v[62:63]
	v_cvt_pk_bf16_f32 v48, v52, v53
	v_pk_add_f32 v[54:55], v[54:55], v[58:59]
	v_lshlrev_b32_e32 v52, 16, v48
	v_cvt_pk_bf16_f32 v49, v54, v55
	v_cvt_pk_bf16_f32 v50, v50, v51
	v_cvt_pk_bf16_f32 v51, v56, v57
	global_store_dwordx4 v[60:61], v[48:51], off offset:256 nt
	s_nop 1
	v_and_b32_e32 v48, 0xffff0000, v48
	v_mul_f32_e32 v48, v48, v48
	v_fmac_f32_e32 v48, v52, v52
	v_lshlrev_b32_e32 v52, 16, v49
	v_and_b32_e32 v49, 0xffff0000, v49
	v_mul_f32_e32 v49, v49, v49
	v_add_f32_e32 v48, v82, v48
	v_fmac_f32_e32 v49, v52, v52
	v_add_f32_e32 v48, v48, v49
	v_lshlrev_b32_e32 v49, 16, v50
	v_and_b32_e32 v50, 0xffff0000, v50
	v_mul_f32_e32 v50, v50, v50
	v_fmac_f32_e32 v50, v49, v49
	v_add_f32_e32 v48, v48, v50
	v_and_b32_e32 v50, 0xffff0000, v51
	v_lshlrev_b32_e32 v49, 16, v51
	v_mul_f32_e32 v50, v50, v50
	v_fmac_f32_e32 v50, v49, v49
	v_add_f32_e32 v48, v48, v50
	v_mov_b32_e32 v49, v48
	s_nop 1
	v_permlane16_swap_b32_e32 v49, v48
	s_waitcnt lgkmcnt(0)
	v_add_f32_e32 v48, v48, v49
	v_mov_b32_e32 v49, v48
	s_nop 1
	v_permlane32_swap_b32_e32 v49, v48
	s_and_saveexec_b64 s[6:7], vcc
	s_cbranch_execz .LBB0_346
	s_waitcnt lgkmcnt(0)
	v_add_f32_e32 v50, v48, v49
	v_lshlrev_b64 v[48:49], 6, v[80:81]
	v_lshl_add_u64 v[48:49], s[46:47], 0, v[48:49]
	v_lshl_add_u64 v[48:49], s[56:57], 2, v[48:49]
	s_lshl_b32 s38, s8, 2
	v_lshl_add_u64 v[48:49], v[48:49], 0, s[38:39]
	flat_store_dword v[48:49], v50 sc0 sc1
.LBB0_346:
	s_or_b64 exec, exec, s[6:7]
	v_lshlrev_b32_e32 v48, 16, v68
	s_waitcnt lgkmcnt(0)
	v_and_b32_e32 v49, 0xffff0000, v68
	v_lshlrev_b32_e32 v52, 16, v70
	v_and_b32_e32 v53, 0xffff0000, v70
	v_lshlrev_b32_e32 v54, 16, v71
	v_and_b32_e32 v55, 0xffff0000, v71
	v_pk_add_f32 v[44:45], v[44:45], v[48:49]
	v_lshlrev_b32_e32 v50, 16, v69
	v_and_b32_e32 v51, 0xffff0000, v69
	v_pk_add_f32 v[48:49], v[42:43], v[54:55]
	v_pk_add_f32 v[42:43], v[40:41], v[52:53]
	v_cvt_pk_bf16_f32 v40, v44, v45
	v_lshl_add_u64 v[44:45], s[68:69], 0, v[78:79]
	v_pk_add_f32 v[46:47], v[46:47], v[50:51]
	v_lshl_add_u64 v[44:45], v[168:169], 1, v[44:45]
	v_cvt_pk_bf16_f32 v41, v46, v47
	v_cvt_pk_bf16_f32 v42, v42, v43
	v_cvt_pk_bf16_f32 v43, v48, v49
	global_store_dwordx4 v[44:45], v[40:43], off nt
	v_lshlrev_b32_e32 v46, 16, v40
	v_and_b32_e32 v47, 0xffff0000, v66
	v_and_b32_e32 v40, 0xffff0000, v40
	v_mul_f32_e32 v40, v40, v40
	v_fmac_f32_e32 v40, v46, v46
	v_lshlrev_b32_e32 v46, 16, v41
	v_and_b32_e32 v41, 0xffff0000, v41
	v_mul_f32_e32 v41, v41, v41
	v_fmac_f32_e32 v41, v46, v46
	v_add_f32_e32 v40, v40, v41
	v_lshlrev_b32_e32 v41, 16, v42
	v_and_b32_e32 v42, 0xffff0000, v42
	v_mul_f32_e32 v42, v42, v42
	v_fmac_f32_e32 v42, v41, v41
	v_add_f32_e32 v40, v40, v42
	v_and_b32_e32 v42, 0xffff0000, v43
	v_lshlrev_b32_e32 v41, 16, v43
	v_mul_f32_e32 v42, v42, v42
	v_fmac_f32_e32 v42, v41, v41
	v_add_f32_e32 v50, v40, v42
	v_lshlrev_b32_e32 v40, 16, v64
	v_and_b32_e32 v41, 0xffff0000, v64
	v_lshlrev_b32_e32 v46, 16, v66
	v_lshlrev_b32_e32 v42, 16, v65
	v_and_b32_e32 v43, 0xffff0000, v65
	v_lshlrev_b32_e32 v48, 16, v67
	v_and_b32_e32 v49, 0xffff0000, v67
	v_pk_add_f32 v[36:37], v[36:37], v[40:41]
	v_pk_add_f32 v[32:33], v[32:33], v[46:47]
	v_pk_add_f32 v[38:39], v[38:39], v[42:43]
	v_pk_add_f32 v[40:41], v[34:35], v[48:49]
	v_cvt_pk_bf16_f32 v34, v36, v37
	v_cvt_pk_bf16_f32 v35, v38, v39
	v_cvt_pk_bf16_f32 v36, v32, v33
	s_nop 0
	v_and_b32_e32 v33, 0xffff0000, v34
	v_lshlrev_b32_e32 v32, 16, v34
	v_mul_f32_e32 v33, v33, v33
	v_fmac_f32_e32 v33, v32, v32
	v_and_b32_e32 v38, 0xffff0000, v35
	v_add_f32_e32 v32, v50, v33
	v_lshlrev_b32_e32 v33, 16, v35
	v_mul_f32_e32 v38, v38, v38
	v_fmac_f32_e32 v38, v33, v33
	v_add_f32_e32 v32, v32, v38
	v_and_b32_e32 v38, 0xffff0000, v36
	v_lshlrev_b32_e32 v33, 16, v36
	v_mul_f32_e32 v38, v38, v38
	v_fmac_f32_e32 v38, v33, v33
	v_cvt_pk_bf16_f32 v37, v40, v41
	v_add_f32_e32 v32, v32, v38
	v_and_b32_e32 v38, 0xffff0000, v37
	v_lshlrev_b32_e32 v33, 16, v37
	v_mul_f32_e32 v38, v38, v38
	v_fmac_f32_e32 v38, v33, v33
	v_add_f32_e32 v32, v32, v38
	v_mov_b32_e32 v33, v32
	s_nop 1
	v_permlane16_swap_b32_e32 v33, v32
	global_store_dwordx4 v[44:45], v[34:37], off offset:256 nt
	s_waitcnt lgkmcnt(0)
	v_add_f32_e32 v32, v32, v33
	v_mov_b32_e32 v33, v32
	s_nop 1
	v_permlane32_swap_b32_e32 v33, v32
	s_and_saveexec_b64 s[6:7], vcc
	s_cbranch_execz .LBB0_348
	s_waitcnt lgkmcnt(0)
	v_add_f32_e32 v34, v32, v33
	v_lshlrev_b64 v[32:33], 6, v[76:77]
	v_lshl_add_u64 v[32:33], s[46:47], 0, v[32:33]
	v_lshl_add_u64 v[32:33], s[56:57], 2, v[32:33]
	s_lshl_b32 s38, s8, 2
	v_lshl_add_u64 v[32:33], v[32:33], 0, s[38:39]
	flat_store_dword v[32:33], v34 sc0 sc1
.LBB0_348:
	s_or_b64 exec, exec, s[6:7]
	v_add_u32_e32 v48, 0xa0, v170
	v_ashrrev_i32_e32 v49, 31, v48
	v_lshlrev_b64 v[54:55], 11, v[48:49]
	s_waitcnt lgkmcnt(0)
	v_lshl_add_u64 v[32:33], v[172:173], 0, v[54:55]
	global_load_dwordx4 v[50:53], v[32:33], off
	global_load_dwordx4 v[40:43], v[32:33], off offset:256
	v_add_u32_e32 v44, 0xb0, v170
	v_ashrrev_i32_e32 v45, 31, v44
	v_lshlrev_b64 v[46:47], 11, v[44:45]
	v_lshl_add_u64 v[32:33], v[172:173], 0, v[46:47]
	global_load_dwordx4 v[36:39], v[32:33], off
	s_nop 0
	global_load_dwordx4 v[32:35], v[32:33], off offset:256
	s_waitcnt vmcnt(0)
	v_lshlrev_b32_e32 v56, 16, v50
	v_and_b32_e32 v57, 0xffff0000, v50
	v_lshlrev_b32_e32 v50, 16, v51
	v_and_b32_e32 v51, 0xffff0000, v51
	v_lshlrev_b32_e32 v58, 16, v52
	v_and_b32_e32 v59, 0xffff0000, v52
	v_lshlrev_b32_e32 v52, 16, v53
	v_and_b32_e32 v53, 0xffff0000, v53
	v_pk_add_f32 v[28:29], v[28:29], v[56:57]
	v_pk_add_f32 v[30:31], v[30:31], v[50:51]
	v_pk_add_f32 v[50:51], v[26:27], v[52:53]
	v_pk_add_f32 v[26:27], v[24:25], v[58:59]
	v_cvt_pk_bf16_f32 v24, v28, v29
	v_lshl_add_u64 v[28:29], s[68:69], 0, v[54:55]
	v_lshl_add_u64 v[28:29], v[168:169], 1, v[28:29]
	v_cvt_pk_bf16_f32 v25, v30, v31
	v_cvt_pk_bf16_f32 v26, v26, v27
	v_cvt_pk_bf16_f32 v27, v50, v51
	global_store_dwordx4 v[28:29], v[24:27], off nt
	v_lshlrev_b32_e32 v30, 16, v24
	v_and_b32_e32 v31, 0xffff0000, v42
	v_and_b32_e32 v24, 0xffff0000, v24
	v_mul_f32_e32 v24, v24, v24
	v_fmac_f32_e32 v24, v30, v30
	v_lshlrev_b32_e32 v30, 16, v25
	v_and_b32_e32 v25, 0xffff0000, v25
	v_mul_f32_e32 v25, v25, v25
	v_fmac_f32_e32 v25, v30, v30
	v_add_f32_e32 v24, v24, v25
	v_lshlrev_b32_e32 v25, 16, v26
	v_and_b32_e32 v26, 0xffff0000, v26
	v_mul_f32_e32 v26, v26, v26
	v_fmac_f32_e32 v26, v25, v25
	v_add_f32_e32 v24, v24, v26
	v_and_b32_e32 v26, 0xffff0000, v27
	v_lshlrev_b32_e32 v25, 16, v27
	v_mul_f32_e32 v26, v26, v26
	v_fmac_f32_e32 v26, v25, v25
	v_add_f32_e32 v50, v24, v26
	v_lshlrev_b32_e32 v24, 16, v40
	v_and_b32_e32 v25, 0xffff0000, v40
	v_lshlrev_b32_e32 v26, 16, v41
	v_and_b32_e32 v27, 0xffff0000, v41
	v_lshlrev_b32_e32 v30, 16, v42
	v_lshlrev_b32_e32 v40, 16, v43
	v_and_b32_e32 v41, 0xffff0000, v43
	v_pk_add_f32 v[20:21], v[20:21], v[24:25]
	v_pk_add_f32 v[24:25], v[18:19], v[40:41]
	v_pk_add_f32 v[18:19], v[16:17], v[30:31]
	v_cvt_pk_bf16_f32 v16, v20, v21
	v_pk_add_f32 v[22:23], v[22:23], v[26:27]
	v_lshlrev_b32_e32 v20, 16, v16
	v_cvt_pk_bf16_f32 v17, v22, v23
	v_cvt_pk_bf16_f32 v18, v18, v19
	v_cvt_pk_bf16_f32 v19, v24, v25
	global_store_dwordx4 v[28:29], v[16:19], off offset:256 nt
	s_nop 1
	v_and_b32_e32 v16, 0xffff0000, v16
	v_mul_f32_e32 v16, v16, v16
	v_fmac_f32_e32 v16, v20, v20
	v_lshlrev_b32_e32 v20, 16, v17
	v_and_b32_e32 v17, 0xffff0000, v17
	v_mul_f32_e32 v17, v17, v17
	v_add_f32_e32 v16, v50, v16
	v_fmac_f32_e32 v17, v20, v20
	v_add_f32_e32 v16, v16, v17
	v_lshlrev_b32_e32 v17, 16, v18
	v_and_b32_e32 v18, 0xffff0000, v18
	v_mul_f32_e32 v18, v18, v18
	v_fmac_f32_e32 v18, v17, v17
	v_add_f32_e32 v16, v16, v18
	v_and_b32_e32 v18, 0xffff0000, v19
	v_lshlrev_b32_e32 v17, 16, v19
	v_mul_f32_e32 v18, v18, v18
	v_fmac_f32_e32 v18, v17, v17
	v_add_f32_e32 v16, v16, v18
	v_mov_b32_e32 v17, v16
	s_nop 1
	v_permlane16_swap_b32_e32 v17, v16
	s_waitcnt lgkmcnt(0)
	v_add_f32_e32 v16, v16, v17
	v_mov_b32_e32 v17, v16
	s_nop 1
	v_permlane32_swap_b32_e32 v17, v16
	s_and_saveexec_b64 s[6:7], vcc
	s_cbranch_execz .LBB0_350
	s_waitcnt lgkmcnt(0)
	v_add_f32_e32 v18, v16, v17
	v_lshlrev_b64 v[16:17], 6, v[48:49]
	v_lshl_add_u64 v[16:17], s[46:47], 0, v[16:17]
	v_lshl_add_u64 v[16:17], s[56:57], 2, v[16:17]
	s_lshl_b32 s38, s8, 2
	v_lshl_add_u64 v[16:17], v[16:17], 0, s[38:39]
	flat_store_dword v[16:17], v18 sc0 sc1
.LBB0_350:
	s_or_b64 exec, exec, s[6:7]
	v_lshlrev_b32_e32 v16, 16, v36
	s_waitcnt lgkmcnt(0)
	v_and_b32_e32 v17, 0xffff0000, v36
	v_lshlrev_b32_e32 v20, 16, v38
	v_and_b32_e32 v21, 0xffff0000, v38
	v_lshlrev_b32_e32 v22, 16, v39
	v_and_b32_e32 v23, 0xffff0000, v39
	v_pk_add_f32 v[12:13], v[12:13], v[16:17]
	v_lshlrev_b32_e32 v18, 16, v37
	v_and_b32_e32 v19, 0xffff0000, v37
	v_pk_add_f32 v[16:17], v[10:11], v[22:23]
	v_pk_add_f32 v[10:11], v[8:9], v[20:21]
	v_cvt_pk_bf16_f32 v8, v12, v13
	v_lshl_add_u64 v[12:13], s[68:69], 0, v[46:47]
	v_pk_add_f32 v[14:15], v[14:15], v[18:19]
	v_lshl_add_u64 v[12:13], v[168:169], 1, v[12:13]
	v_cvt_pk_bf16_f32 v9, v14, v15
	v_cvt_pk_bf16_f32 v10, v10, v11
	v_cvt_pk_bf16_f32 v11, v16, v17
	global_store_dwordx4 v[12:13], v[8:11], off nt
	v_lshlrev_b32_e32 v14, 16, v8
	v_and_b32_e32 v15, 0xffff0000, v34
	v_and_b32_e32 v8, 0xffff0000, v8
	v_mul_f32_e32 v8, v8, v8
	v_fmac_f32_e32 v8, v14, v14
	v_lshlrev_b32_e32 v14, 16, v9
	v_and_b32_e32 v9, 0xffff0000, v9
	v_mul_f32_e32 v9, v9, v9
	v_fmac_f32_e32 v9, v14, v14
	v_add_f32_e32 v8, v8, v9
	v_lshlrev_b32_e32 v9, 16, v10
	v_and_b32_e32 v10, 0xffff0000, v10
	v_mul_f32_e32 v10, v10, v10
	v_fmac_f32_e32 v10, v9, v9
	v_add_f32_e32 v8, v8, v10
	v_and_b32_e32 v10, 0xffff0000, v11
	v_lshlrev_b32_e32 v9, 16, v11
	v_mul_f32_e32 v10, v10, v10
	v_fmac_f32_e32 v10, v9, v9
	v_add_f32_e32 v18, v8, v10
	v_lshlrev_b32_e32 v8, 16, v32
	v_and_b32_e32 v9, 0xffff0000, v32
	v_lshlrev_b32_e32 v14, 16, v34
	v_lshlrev_b32_e32 v10, 16, v33
	v_and_b32_e32 v11, 0xffff0000, v33
	v_lshlrev_b32_e32 v16, 16, v35
	v_and_b32_e32 v17, 0xffff0000, v35
	v_pk_add_f32 v[4:5], v[4:5], v[8:9]
	v_pk_add_f32 v[0:1], v[0:1], v[14:15]
	v_pk_add_f32 v[6:7], v[6:7], v[10:11]
	v_pk_add_f32 v[8:9], v[2:3], v[16:17]
	v_cvt_pk_bf16_f32 v2, v4, v5
	v_cvt_pk_bf16_f32 v3, v6, v7
	v_cvt_pk_bf16_f32 v4, v0, v1
	s_nop 0
	v_and_b32_e32 v1, 0xffff0000, v2
	v_lshlrev_b32_e32 v0, 16, v2
	v_mul_f32_e32 v1, v1, v1
	v_fmac_f32_e32 v1, v0, v0
	v_and_b32_e32 v6, 0xffff0000, v3
	v_add_f32_e32 v0, v18, v1
	v_lshlrev_b32_e32 v1, 16, v3
	v_mul_f32_e32 v6, v6, v6
	v_fmac_f32_e32 v6, v1, v1
	v_add_f32_e32 v0, v0, v6
	v_and_b32_e32 v6, 0xffff0000, v4
	v_lshlrev_b32_e32 v1, 16, v4
	v_mul_f32_e32 v6, v6, v6
	v_fmac_f32_e32 v6, v1, v1
	v_cvt_pk_bf16_f32 v5, v8, v9
	v_add_f32_e32 v0, v0, v6
	v_and_b32_e32 v6, 0xffff0000, v5
	v_lshlrev_b32_e32 v1, 16, v5
	v_mul_f32_e32 v6, v6, v6
	v_fmac_f32_e32 v6, v1, v1
	v_add_f32_e32 v0, v0, v6
	v_mov_b32_e32 v1, v0
	s_nop 1
	v_permlane16_swap_b32_e32 v1, v0
	global_store_dwordx4 v[12:13], v[2:5], off offset:256 nt
	s_waitcnt lgkmcnt(0)
	v_add_f32_e32 v0, v0, v1
	v_mov_b32_e32 v1, v0
	s_nop 1
	v_permlane32_swap_b32_e32 v1, v0
	s_and_saveexec_b64 s[6:7], vcc
	s_cbranch_execz .LBB0_352
	s_waitcnt lgkmcnt(0)
	v_add_f32_e32 v2, v0, v1
	v_lshlrev_b64 v[0:1], 6, v[44:45]
	v_lshl_add_u64 v[0:1], s[46:47], 0, v[0:1]
	v_lshl_add_u64 v[0:1], s[56:57], 2, v[0:1]
	s_lshl_b32 s38, s8, 2
	v_lshl_add_u64 v[0:1], v[0:1], 0, s[38:39]
	flat_store_dword v[0:1], v2 sc0 sc1

.LBB0_378:
	s_mov_b32 s6, -1
	s_lshl_b32 s5, s5, 8
	v_mbcnt_lo_u32_b32 v128, s6, 0
	v_mbcnt_hi_u32_b32 v128, s6, v128
	s_getreg_b32 s6, hwreg(HW_REG_HW_ID, 0, 6)
	s_and_b32 s6, s6, 63
	s_lshl_b32 s6, s6, 2
	s_add_i32 s6, s6, 0
	s_add_i32 s6, s6, 0x20200
	v_mov_b32_e32 v129, s6
	ds_read_b32 v129, v129
	v_bfrev_b32_e32 v130, 0.5
	s_lshl_b32 s56, s4, 2
	s_ashr_i32 s57, s56, 31
	s_waitcnt lgkmcnt(0)
	v_readfirstlane_b32 s6, v129
	s_nop 1
	v_lshl_add_u32 v128, s6, 6, v128
	s_nop 0
	v_readfirstlane_b32 s6, v128
	s_bfe_u32 s8, s6, 0x20006
	s_ashr_i32 s6, s6, 2
	s_andn2_b32 s6, s6, 63
	s_add_i32 s6, s6, s5
	v_and_or_b32 v170, v128, 15, s6
	s_lshl_b32 s5, s4, 8
	s_lshl_b32 s6, s8, 5
	v_bfe_u32 v129, v128, 4, 2
	s_or_b32 s5, s6, s5
	v_lshl_or_b32 v168, v129, 3, s5
	v_ashrrev_i32_e32 v169, 31, v168
	v_lshlrev_b64 v[146:147], 1, v[168:169]
	v_ashrrev_i32_e32 v171, 31, v170
	v_lshlrev_b32_e32 v128, 2, v128
	v_lshl_add_u64 v[172:173], s[68:69], 0, v[146:147]
	v_lshlrev_b64 v[148:149], 11, v[170:171]
	v_bitop3_b32 v181, v128, 64, v130 bitop3:0x6c
	v_bitop3_b32 v180, v128, s84, v130 bitop3:0x6c
	v_cmp_eq_u32_e32 vcc, 0, v129
	v_lshl_add_u64 v[128:129], v[172:173], 0, v[148:149]
	global_load_dwordx4 v[142:145], v[128:129], off
	global_load_dwordx4 v[136:139], v[128:129], off offset:256
	v_or_b32_e32 v174, 16, v170
	v_ashrrev_i32_e32 v175, 31, v174
	v_lshlrev_b64 v[176:177], 11, v[174:175]
	v_lshl_add_u64 v[128:129], v[172:173], 0, v[176:177]
	global_load_dwordx4 v[132:135], v[128:129], off
	s_nop 0
	global_load_dwordx4 v[128:131], v[128:129], off offset:256
	s_waitcnt vmcnt(0)
	v_lshlrev_b32_e32 v150, 16, v142
	v_and_b32_e32 v151, 0xffff0000, v142
	v_lshlrev_b32_e32 v142, 16, v143
	v_and_b32_e32 v143, 0xffff0000, v143
	v_lshlrev_b32_e32 v152, 16, v144
	v_and_b32_e32 v153, 0xffff0000, v144
	v_lshlrev_b32_e32 v144, 16, v145
	v_and_b32_e32 v145, 0xffff0000, v145
	v_pk_add_f32 v[124:125], v[124:125], v[150:151]
	v_pk_add_f32 v[126:127], v[126:127], v[142:143]
	v_pk_add_f32 v[142:143], v[122:123], v[144:145]
	v_pk_add_f32 v[122:123], v[120:121], v[152:153]
	v_cvt_pk_bf16_f32 v120, v124, v125
	v_lshl_add_u64 v[124:125], s[68:69], 0, v[148:149]
	v_lshl_add_u64 v[124:125], v[124:125], 0, v[146:147]
	v_cvt_pk_bf16_f32 v121, v126, v127
	v_cvt_pk_bf16_f32 v122, v122, v123
	v_cvt_pk_bf16_f32 v123, v142, v143
	global_store_dwordx4 v[124:125], v[120:123], off nt
	v_lshlrev_b32_e32 v126, 16, v120
	v_and_b32_e32 v127, 0xffff0000, v138
	v_and_b32_e32 v120, 0xffff0000, v120
	v_mul_f32_e32 v120, v120, v120
	v_fmac_f32_e32 v120, v126, v126
	v_lshlrev_b32_e32 v126, 16, v121
	v_and_b32_e32 v121, 0xffff0000, v121
	v_mul_f32_e32 v121, v121, v121
	v_fmac_f32_e32 v121, v126, v126
	v_add_f32_e32 v120, v120, v121
	v_lshlrev_b32_e32 v121, 16, v122
	v_and_b32_e32 v122, 0xffff0000, v122
	v_mul_f32_e32 v122, v122, v122
	v_fmac_f32_e32 v122, v121, v121
	v_add_f32_e32 v120, v120, v122
	v_and_b32_e32 v122, 0xffff0000, v123
	v_lshlrev_b32_e32 v121, 16, v123
	v_mul_f32_e32 v122, v122, v122
	v_fmac_f32_e32 v122, v121, v121
	v_add_f32_e32 v142, v120, v122
	v_lshlrev_b32_e32 v120, 16, v136
	v_and_b32_e32 v121, 0xffff0000, v136
	v_lshlrev_b32_e32 v122, 16, v137
	v_and_b32_e32 v123, 0xffff0000, v137
	v_lshlrev_b32_e32 v126, 16, v138
	v_lshlrev_b32_e32 v136, 16, v139
	v_and_b32_e32 v137, 0xffff0000, v139
	v_pk_add_f32 v[116:117], v[116:117], v[120:121]
	v_pk_add_f32 v[120:121], v[114:115], v[136:137]
	v_pk_add_f32 v[114:115], v[112:113], v[126:127]
	v_cvt_pk_bf16_f32 v112, v116, v117
	v_pk_add_f32 v[118:119], v[118:119], v[122:123]
	v_lshlrev_b32_e32 v116, 16, v112
	v_cvt_pk_bf16_f32 v113, v118, v119
	v_cvt_pk_bf16_f32 v114, v114, v115
	v_cvt_pk_bf16_f32 v115, v120, v121
	global_store_dwordx4 v[124:125], v[112:115], off offset:256 nt
	s_nop 1
	v_and_b32_e32 v112, 0xffff0000, v112
	v_mul_f32_e32 v112, v112, v112
	v_fmac_f32_e32 v112, v116, v116
	v_lshlrev_b32_e32 v116, 16, v113
	v_and_b32_e32 v113, 0xffff0000, v113
	v_mul_f32_e32 v113, v113, v113
	v_add_f32_e32 v112, v142, v112
	v_fmac_f32_e32 v113, v116, v116
	v_add_f32_e32 v112, v112, v113
	v_lshlrev_b32_e32 v113, 16, v114
	v_and_b32_e32 v114, 0xffff0000, v114
	v_mul_f32_e32 v114, v114, v114
	v_fmac_f32_e32 v114, v113, v113
	v_add_f32_e32 v112, v112, v114
	v_and_b32_e32 v114, 0xffff0000, v115
	v_lshlrev_b32_e32 v113, 16, v115
	v_mul_f32_e32 v114, v114, v114
	v_fmac_f32_e32 v114, v113, v113
	v_add_f32_e32 v112, v112, v114
	v_mov_b32_e32 v113, v112
	s_nop 1
	v_permlane16_swap_b32_e32 v113, v112
	s_waitcnt lgkmcnt(0)
	v_add_f32_e32 v112, v112, v113
	v_mov_b32_e32 v113, v112
	s_nop 1
	v_permlane32_swap_b32_e32 v113, v112
	s_and_saveexec_b64 s[6:7], vcc
	s_cbranch_execz .LBB0_380
	v_lshlrev_b64 v[114:115], 6, v[170:171]
	v_lshl_add_u64 v[114:115], s[46:47], 0, v[114:115]
	v_lshl_add_u64 v[114:115], s[56:57], 2, v[114:115]
	s_lshl_b32 s38, s8, 2
	v_lshl_add_u64 v[114:115], v[114:115], 0, s[38:39]
	s_waitcnt lgkmcnt(0)
	v_add_f32_e32 v112, v112, v113
	flat_store_dword v[114:115], v112 sc0 sc1
.LBB0_380:
	s_or_b64 exec, exec, s[6:7]
	v_lshlrev_b32_e32 v112, 16, v132
	s_waitcnt lgkmcnt(0)
	v_and_b32_e32 v113, 0xffff0000, v132
	v_lshlrev_b32_e32 v116, 16, v134
	v_and_b32_e32 v117, 0xffff0000, v134
	v_lshlrev_b32_e32 v118, 16, v135
	v_and_b32_e32 v119, 0xffff0000, v135
	v_pk_add_f32 v[108:109], v[108:109], v[112:113]
	v_lshlrev_b32_e32 v114, 16, v133
	v_and_b32_e32 v115, 0xffff0000, v133
	v_pk_add_f32 v[112:113], v[106:107], v[118:119]
	v_pk_add_f32 v[106:107], v[104:105], v[116:117]
	v_cvt_pk_bf16_f32 v104, v108, v109
	v_lshl_add_u64 v[108:109], s[68:69], 0, v[176:177]
	v_pk_add_f32 v[110:111], v[110:111], v[114:115]
	v_lshl_add_u64 v[108:109], v[168:169], 1, v[108:109]
	v_cvt_pk_bf16_f32 v105, v110, v111
	v_cvt_pk_bf16_f32 v106, v106, v107
	v_cvt_pk_bf16_f32 v107, v112, v113
	global_store_dwordx4 v[108:109], v[104:107], off nt
	v_lshlrev_b32_e32 v110, 16, v104
	v_and_b32_e32 v111, 0xffff0000, v130
	v_and_b32_e32 v104, 0xffff0000, v104
	v_mul_f32_e32 v104, v104, v104
	v_fmac_f32_e32 v104, v110, v110
	v_lshlrev_b32_e32 v110, 16, v105
	v_and_b32_e32 v105, 0xffff0000, v105
	v_mul_f32_e32 v105, v105, v105
	v_fmac_f32_e32 v105, v110, v110
	v_add_f32_e32 v104, v104, v105
	v_lshlrev_b32_e32 v105, 16, v106
	v_and_b32_e32 v106, 0xffff0000, v106
	v_mul_f32_e32 v106, v106, v106
	v_fmac_f32_e32 v106, v105, v105
	v_add_f32_e32 v104, v104, v106
	v_and_b32_e32 v106, 0xffff0000, v107
	v_lshlrev_b32_e32 v105, 16, v107
	v_mul_f32_e32 v106, v106, v106
	v_fmac_f32_e32 v106, v105, v105
	v_add_f32_e32 v114, v104, v106
	v_lshlrev_b32_e32 v104, 16, v128
	v_and_b32_e32 v105, 0xffff0000, v128
	v_lshlrev_b32_e32 v110, 16, v130
	v_lshlrev_b32_e32 v106, 16, v129
	v_and_b32_e32 v107, 0xffff0000, v129
	v_lshlrev_b32_e32 v112, 16, v131
	v_and_b32_e32 v113, 0xffff0000, v131
	v_pk_add_f32 v[100:101], v[100:101], v[104:105]
	v_pk_add_f32 v[96:97], v[96:97], v[110:111]
	v_pk_add_f32 v[102:103], v[102:103], v[106:107]
	v_pk_add_f32 v[104:105], v[98:99], v[112:113]
	v_cvt_pk_bf16_f32 v98, v100, v101
	v_cvt_pk_bf16_f32 v99, v102, v103
	v_cvt_pk_bf16_f32 v100, v96, v97
	s_nop 0
	v_and_b32_e32 v97, 0xffff0000, v98
	v_lshlrev_b32_e32 v96, 16, v98
	v_mul_f32_e32 v97, v97, v97
	v_fmac_f32_e32 v97, v96, v96
	v_and_b32_e32 v102, 0xffff0000, v99
	v_add_f32_e32 v96, v114, v97
	v_lshlrev_b32_e32 v97, 16, v99
	v_mul_f32_e32 v102, v102, v102
	v_fmac_f32_e32 v102, v97, v97
	v_add_f32_e32 v96, v96, v102
	v_and_b32_e32 v102, 0xffff0000, v100
	v_lshlrev_b32_e32 v97, 16, v100
	v_mul_f32_e32 v102, v102, v102
	v_fmac_f32_e32 v102, v97, v97
	v_cvt_pk_bf16_f32 v101, v104, v105
	v_add_f32_e32 v96, v96, v102
	v_and_b32_e32 v102, 0xffff0000, v101
	v_lshlrev_b32_e32 v97, 16, v101
	v_mul_f32_e32 v102, v102, v102
	v_fmac_f32_e32 v102, v97, v97
	v_add_f32_e32 v96, v96, v102
	v_mov_b32_e32 v97, v96
	s_nop 1
	v_permlane16_swap_b32_e32 v97, v96
	global_store_dwordx4 v[108:109], v[98:101], off offset:256 nt
	s_waitcnt lgkmcnt(0)
	v_add_f32_e32 v96, v96, v97
	v_mov_b32_e32 v97, v96
	s_nop 1
	v_permlane32_swap_b32_e32 v97, v96
	s_and_saveexec_b64 s[6:7], vcc
	s_cbranch_execz .LBB0_382
	v_lshlrev_b64 v[98:99], 6, v[174:175]
	v_lshl_add_u64 v[98:99], s[46:47], 0, v[98:99]
	v_lshl_add_u64 v[98:99], s[56:57], 2, v[98:99]
	s_lshl_b32 s38, s8, 2
	v_lshl_add_u64 v[98:99], v[98:99], 0, s[38:39]
	s_waitcnt lgkmcnt(0)
	v_add_f32_e32 v96, v96, v97
	flat_store_dword v[98:99], v96 sc0 sc1
.LBB0_382:
	s_or_b64 exec, exec, s[6:7]
	v_or_b32_e32 v112, 32, v170
	v_ashrrev_i32_e32 v113, 31, v112
	v_lshlrev_b64 v[118:119], 11, v[112:113]
	s_waitcnt lgkmcnt(0)
	v_lshl_add_u64 v[96:97], v[172:173], 0, v[118:119]
	global_load_dwordx4 v[114:117], v[96:97], off
	global_load_dwordx4 v[104:107], v[96:97], off offset:256
	v_or_b32_e32 v108, 48, v170
	v_ashrrev_i32_e32 v109, 31, v108
	v_lshlrev_b64 v[110:111], 11, v[108:109]
	v_lshl_add_u64 v[96:97], v[172:173], 0, v[110:111]
	global_load_dwordx4 v[100:103], v[96:97], off
	s_nop 0
	global_load_dwordx4 v[96:99], v[96:97], off offset:256
	s_waitcnt vmcnt(0)
	v_lshlrev_b32_e32 v120, 16, v114
	v_and_b32_e32 v121, 0xffff0000, v114
	v_lshlrev_b32_e32 v114, 16, v115
	v_and_b32_e32 v115, 0xffff0000, v115
	v_lshlrev_b32_e32 v122, 16, v116
	v_and_b32_e32 v123, 0xffff0000, v116
	v_lshlrev_b32_e32 v116, 16, v117
	v_and_b32_e32 v117, 0xffff0000, v117
	v_pk_add_f32 v[92:93], v[92:93], v[120:121]
	v_pk_add_f32 v[94:95], v[94:95], v[114:115]
	v_pk_add_f32 v[114:115], v[90:91], v[116:117]
	v_pk_add_f32 v[90:91], v[88:89], v[122:123]
	v_cvt_pk_bf16_f32 v88, v92, v93
	v_lshl_add_u64 v[92:93], s[68:69], 0, v[118:119]
	v_lshl_add_u64 v[92:93], v[168:169], 1, v[92:93]
	v_cvt_pk_bf16_f32 v89, v94, v95
	v_cvt_pk_bf16_f32 v90, v90, v91
	v_cvt_pk_bf16_f32 v91, v114, v115
	global_store_dwordx4 v[92:93], v[88:91], off nt
	v_lshlrev_b32_e32 v94, 16, v88
	v_and_b32_e32 v95, 0xffff0000, v106
	v_and_b32_e32 v88, 0xffff0000, v88
	v_mul_f32_e32 v88, v88, v88
	v_fmac_f32_e32 v88, v94, v94
	v_lshlrev_b32_e32 v94, 16, v89
	v_and_b32_e32 v89, 0xffff0000, v89
	v_mul_f32_e32 v89, v89, v89
	v_fmac_f32_e32 v89, v94, v94
	v_add_f32_e32 v88, v88, v89
	v_lshlrev_b32_e32 v89, 16, v90
	v_and_b32_e32 v90, 0xffff0000, v90
	v_mul_f32_e32 v90, v90, v90
	v_fmac_f32_e32 v90, v89, v89
	v_add_f32_e32 v88, v88, v90
	v_and_b32_e32 v90, 0xffff0000, v91
	v_lshlrev_b32_e32 v89, 16, v91
	v_mul_f32_e32 v90, v90, v90
	v_fmac_f32_e32 v90, v89, v89
	v_add_f32_e32 v114, v88, v90
	v_lshlrev_b32_e32 v88, 16, v104
	v_and_b32_e32 v89, 0xffff0000, v104
	v_lshlrev_b32_e32 v90, 16, v105
	v_and_b32_e32 v91, 0xffff0000, v105
	v_lshlrev_b32_e32 v94, 16, v106
	v_lshlrev_b32_e32 v104, 16, v107
	v_and_b32_e32 v105, 0xffff0000, v107
	v_pk_add_f32 v[84:85], v[84:85], v[88:89]
	v_pk_add_f32 v[88:89], v[82:83], v[104:105]
	v_pk_add_f32 v[82:83], v[80:81], v[94:95]
	v_cvt_pk_bf16_f32 v80, v84, v85
	v_pk_add_f32 v[86:87], v[86:87], v[90:91]
	v_lshlrev_b32_e32 v84, 16, v80
	v_cvt_pk_bf16_f32 v81, v86, v87
	v_cvt_pk_bf16_f32 v82, v82, v83
	v_cvt_pk_bf16_f32 v83, v88, v89
	global_store_dwordx4 v[92:93], v[80:83], off offset:256 nt
	s_nop 1
	v_and_b32_e32 v80, 0xffff0000, v80
	v_mul_f32_e32 v80, v80, v80
	v_fmac_f32_e32 v80, v84, v84
	v_lshlrev_b32_e32 v84, 16, v81
	v_and_b32_e32 v81, 0xffff0000, v81
	v_mul_f32_e32 v81, v81, v81
	v_add_f32_e32 v80, v114, v80
	v_fmac_f32_e32 v81, v84, v84
	v_add_f32_e32 v80, v80, v81
	v_lshlrev_b32_e32 v81, 16, v82
	v_and_b32_e32 v82, 0xffff0000, v82
	v_mul_f32_e32 v82, v82, v82
	v_fmac_f32_e32 v82, v81, v81
	v_add_f32_e32 v80, v80, v82
	v_and_b32_e32 v82, 0xffff0000, v83
	v_lshlrev_b32_e32 v81, 16, v83
	v_mul_f32_e32 v82, v82, v82
	v_fmac_f32_e32 v82, v81, v81
	v_add_f32_e32 v80, v80, v82
	v_mov_b32_e32 v81, v80
	s_nop 1
	v_permlane16_swap_b32_e32 v81, v80
	s_waitcnt lgkmcnt(0)
	v_add_f32_e32 v80, v80, v81
	v_mov_b32_e32 v81, v80
	s_nop 1
	v_permlane32_swap_b32_e32 v81, v80
	s_mov_b64 s[6:7], exec
	s_and_b64 s[4:5], s[6:7], vcc
	v_mov_b32_e32 v198, v220
	v_mov_b32_e32 v199, v221
	v_mov_b32_e32 v248, v222
	v_mov_b32_e32 v205, v223
	v_mov_b32_e32 v196, v224
	s_mov_b64 exec, s[4:5]
	s_cbranch_execz .LBB0_384
	v_lshlrev_b64 v[82:83], 6, v[112:113]
	v_lshl_add_u64 v[82:83], s[46:47], 0, v[82:83]
	v_lshl_add_u64 v[82:83], s[56:57], 2, v[82:83]
	s_lshl_b32 s38, s8, 2
	v_lshl_add_u64 v[82:83], v[82:83], 0, s[38:39]
	s_waitcnt lgkmcnt(0)
	v_add_f32_e32 v80, v80, v81
	flat_store_dword v[82:83], v80 sc0 sc1
.LBB0_384:
	s_or_b64 exec, exec, s[6:7]
	v_lshlrev_b32_e32 v80, 16, v100
	s_waitcnt lgkmcnt(0)
	v_and_b32_e32 v81, 0xffff0000, v100
	v_lshlrev_b32_e32 v84, 16, v102
	v_and_b32_e32 v85, 0xffff0000, v102
	v_lshlrev_b32_e32 v86, 16, v103
	v_and_b32_e32 v87, 0xffff0000, v103
	v_pk_add_f32 v[76:77], v[76:77], v[80:81]
	v_lshlrev_b32_e32 v82, 16, v101
	v_and_b32_e32 v83, 0xffff0000, v101
	v_pk_add_f32 v[80:81], v[74:75], v[86:87]
	v_pk_add_f32 v[74:75], v[72:73], v[84:85]
	v_cvt_pk_bf16_f32 v72, v76, v77
	v_lshl_add_u64 v[76:77], s[68:69], 0, v[110:111]
	v_pk_add_f32 v[78:79], v[78:79], v[82:83]
	v_lshl_add_u64 v[76:77], v[168:169], 1, v[76:77]
	v_cvt_pk_bf16_f32 v73, v78, v79
	v_cvt_pk_bf16_f32 v74, v74, v75
	v_cvt_pk_bf16_f32 v75, v80, v81
	global_store_dwordx4 v[76:77], v[72:75], off nt
	v_lshlrev_b32_e32 v78, 16, v72
	v_and_b32_e32 v79, 0xffff0000, v98
	v_and_b32_e32 v72, 0xffff0000, v72
	v_mul_f32_e32 v72, v72, v72
	v_fmac_f32_e32 v72, v78, v78
	v_lshlrev_b32_e32 v78, 16, v73
	v_and_b32_e32 v73, 0xffff0000, v73
	v_mul_f32_e32 v73, v73, v73
	v_fmac_f32_e32 v73, v78, v78
	v_add_f32_e32 v72, v72, v73
	v_lshlrev_b32_e32 v73, 16, v74
	v_and_b32_e32 v74, 0xffff0000, v74
	v_mul_f32_e32 v74, v74, v74
	v_fmac_f32_e32 v74, v73, v73
	v_add_f32_e32 v72, v72, v74
	v_and_b32_e32 v74, 0xffff0000, v75
	v_lshlrev_b32_e32 v73, 16, v75
	v_mul_f32_e32 v74, v74, v74
	v_fmac_f32_e32 v74, v73, v73
	v_add_f32_e32 v82, v72, v74
	v_lshlrev_b32_e32 v72, 16, v96
	v_and_b32_e32 v73, 0xffff0000, v96
	v_lshlrev_b32_e32 v78, 16, v98
	v_lshlrev_b32_e32 v74, 16, v97
	v_and_b32_e32 v75, 0xffff0000, v97
	v_lshlrev_b32_e32 v80, 16, v99
	v_and_b32_e32 v81, 0xffff0000, v99
	v_pk_add_f32 v[68:69], v[68:69], v[72:73]
	v_pk_add_f32 v[64:65], v[64:65], v[78:79]
	v_pk_add_f32 v[70:71], v[70:71], v[74:75]
	v_pk_add_f32 v[72:73], v[66:67], v[80:81]
	v_cvt_pk_bf16_f32 v66, v68, v69
	v_cvt_pk_bf16_f32 v67, v70, v71
	v_cvt_pk_bf16_f32 v68, v64, v65
	s_nop 0
	v_and_b32_e32 v65, 0xffff0000, v66
	v_lshlrev_b32_e32 v64, 16, v66
	v_mul_f32_e32 v65, v65, v65
	v_fmac_f32_e32 v65, v64, v64
	v_and_b32_e32 v70, 0xffff0000, v67
	v_add_f32_e32 v64, v82, v65
	v_lshlrev_b32_e32 v65, 16, v67
	v_mul_f32_e32 v70, v70, v70
	v_fmac_f32_e32 v70, v65, v65
	v_add_f32_e32 v64, v64, v70
	v_and_b32_e32 v70, 0xffff0000, v68
	v_lshlrev_b32_e32 v65, 16, v68
	v_mul_f32_e32 v70, v70, v70
	v_fmac_f32_e32 v70, v65, v65
	v_cvt_pk_bf16_f32 v69, v72, v73
	v_add_f32_e32 v64, v64, v70
	v_and_b32_e32 v70, 0xffff0000, v69
	v_lshlrev_b32_e32 v65, 16, v69
	v_mul_f32_e32 v70, v70, v70
	v_fmac_f32_e32 v70, v65, v65
	v_add_f32_e32 v64, v64, v70
	v_mov_b32_e32 v65, v64
	s_nop 1
	v_permlane16_swap_b32_e32 v65, v64
	global_store_dwordx4 v[76:77], v[66:69], off offset:256 nt
	s_waitcnt lgkmcnt(0)
	v_add_f32_e32 v64, v64, v65
	v_mov_b32_e32 v65, v64
	s_nop 1
	v_permlane32_swap_b32_e32 v65, v64
	s_and_saveexec_b64 s[6:7], vcc
	s_cbranch_execz .LBB0_386
	v_lshlrev_b64 v[66:67], 6, v[108:109]
	v_lshl_add_u64 v[66:67], s[46:47], 0, v[66:67]
	v_lshl_add_u64 v[66:67], s[56:57], 2, v[66:67]
	s_lshl_b32 s38, s8, 2
	v_lshl_add_u64 v[66:67], v[66:67], 0, s[38:39]
	s_waitcnt lgkmcnt(0)
	v_add_f32_e32 v64, v64, v65
	flat_store_dword v[66:67], v64 sc0 sc1
.LBB0_386:
	s_or_b64 exec, exec, s[6:7]
	v_add_u32_e32 v80, 0x80, v170
	v_ashrrev_i32_e32 v81, 31, v80
	v_lshlrev_b64 v[86:87], 11, v[80:81]
	s_waitcnt lgkmcnt(0)
	v_lshl_add_u64 v[64:65], v[172:173], 0, v[86:87]
	global_load_dwordx4 v[82:85], v[64:65], off
	global_load_dwordx4 v[72:75], v[64:65], off offset:256
	v_add_u32_e32 v76, 0x90, v170
	v_ashrrev_i32_e32 v77, 31, v76
	v_lshlrev_b64 v[78:79], 11, v[76:77]
	v_lshl_add_u64 v[64:65], v[172:173], 0, v[78:79]
	global_load_dwordx4 v[68:71], v[64:65], off
	s_nop 0
	global_load_dwordx4 v[64:67], v[64:65], off offset:256
	s_waitcnt vmcnt(0)
	v_lshlrev_b32_e32 v88, 16, v82
	v_and_b32_e32 v89, 0xffff0000, v82
	v_lshlrev_b32_e32 v82, 16, v83
	v_and_b32_e32 v83, 0xffff0000, v83
	v_lshlrev_b32_e32 v90, 16, v84
	v_and_b32_e32 v91, 0xffff0000, v84
	v_lshlrev_b32_e32 v84, 16, v85
	v_and_b32_e32 v85, 0xffff0000, v85
	v_pk_add_f32 v[60:61], v[60:61], v[88:89]
	v_pk_add_f32 v[62:63], v[62:63], v[82:83]
	v_pk_add_f32 v[82:83], v[58:59], v[84:85]
	v_pk_add_f32 v[58:59], v[56:57], v[90:91]
	v_cvt_pk_bf16_f32 v56, v60, v61
	v_lshl_add_u64 v[60:61], s[68:69], 0, v[86:87]
	v_lshl_add_u64 v[60:61], v[168:169], 1, v[60:61]
	v_cvt_pk_bf16_f32 v57, v62, v63
	v_cvt_pk_bf16_f32 v58, v58, v59
	v_cvt_pk_bf16_f32 v59, v82, v83
	global_store_dwordx4 v[60:61], v[56:59], off nt
	v_lshlrev_b32_e32 v62, 16, v56
	v_and_b32_e32 v63, 0xffff0000, v74
	v_and_b32_e32 v56, 0xffff0000, v56
	v_mul_f32_e32 v56, v56, v56
	v_fmac_f32_e32 v56, v62, v62
	v_lshlrev_b32_e32 v62, 16, v57
	v_and_b32_e32 v57, 0xffff0000, v57
	v_mul_f32_e32 v57, v57, v57
	v_fmac_f32_e32 v57, v62, v62
	v_add_f32_e32 v56, v56, v57
	v_lshlrev_b32_e32 v57, 16, v58
	v_and_b32_e32 v58, 0xffff0000, v58
	v_mul_f32_e32 v58, v58, v58
	v_fmac_f32_e32 v58, v57, v57
	v_add_f32_e32 v56, v56, v58
	v_and_b32_e32 v58, 0xffff0000, v59
	v_lshlrev_b32_e32 v57, 16, v59
	v_mul_f32_e32 v58, v58, v58
	v_fmac_f32_e32 v58, v57, v57
	v_add_f32_e32 v82, v56, v58
	v_lshlrev_b32_e32 v56, 16, v72
	v_and_b32_e32 v57, 0xffff0000, v72
	v_lshlrev_b32_e32 v58, 16, v73
	v_and_b32_e32 v59, 0xffff0000, v73
	v_lshlrev_b32_e32 v62, 16, v74
	v_lshlrev_b32_e32 v72, 16, v75
	v_and_b32_e32 v73, 0xffff0000, v75
	v_pk_add_f32 v[52:53], v[52:53], v[56:57]
	v_pk_add_f32 v[56:57], v[50:51], v[72:73]
	v_pk_add_f32 v[50:51], v[48:49], v[62:63]
	v_cvt_pk_bf16_f32 v48, v52, v53
	v_pk_add_f32 v[54:55], v[54:55], v[58:59]
	v_lshlrev_b32_e32 v52, 16, v48
	v_cvt_pk_bf16_f32 v49, v54, v55
	v_cvt_pk_bf16_f32 v50, v50, v51
	v_cvt_pk_bf16_f32 v51, v56, v57
	global_store_dwordx4 v[60:61], v[48:51], off offset:256 nt
	s_nop 1
	v_and_b32_e32 v48, 0xffff0000, v48
	v_mul_f32_e32 v48, v48, v48
	v_fmac_f32_e32 v48, v52, v52
	v_lshlrev_b32_e32 v52, 16, v49
	v_and_b32_e32 v49, 0xffff0000, v49
	v_mul_f32_e32 v49, v49, v49
	v_add_f32_e32 v48, v82, v48
	v_fmac_f32_e32 v49, v52, v52
	v_add_f32_e32 v48, v48, v49
	v_lshlrev_b32_e32 v49, 16, v50
	v_and_b32_e32 v50, 0xffff0000, v50
	v_mul_f32_e32 v50, v50, v50
	v_fmac_f32_e32 v50, v49, v49
	v_add_f32_e32 v48, v48, v50
	v_and_b32_e32 v50, 0xffff0000, v51
	v_lshlrev_b32_e32 v49, 16, v51
	v_mul_f32_e32 v50, v50, v50
	v_fmac_f32_e32 v50, v49, v49
	v_add_f32_e32 v48, v48, v50
	v_mov_b32_e32 v49, v48
	s_nop 1
	v_permlane16_swap_b32_e32 v49, v48
	s_waitcnt lgkmcnt(0)
	v_add_f32_e32 v48, v48, v49
	v_mov_b32_e32 v49, v48
	s_nop 1
	v_permlane32_swap_b32_e32 v49, v48
	s_and_saveexec_b64 s[6:7], vcc
	s_cbranch_execz .LBB0_388
	v_lshlrev_b64 v[50:51], 6, v[80:81]
	v_lshl_add_u64 v[50:51], s[46:47], 0, v[50:51]
	v_lshl_add_u64 v[50:51], s[56:57], 2, v[50:51]
	s_lshl_b32 s38, s8, 2
	v_lshl_add_u64 v[50:51], v[50:51], 0, s[38:39]
	s_waitcnt lgkmcnt(0)
	v_add_f32_e32 v48, v48, v49
	flat_store_dword v[50:51], v48 sc0 sc1
.LBB0_388:
	s_or_b64 exec, exec, s[6:7]
	v_lshlrev_b32_e32 v48, 16, v68
	s_waitcnt lgkmcnt(0)
	v_and_b32_e32 v49, 0xffff0000, v68
	v_lshlrev_b32_e32 v52, 16, v70
	v_and_b32_e32 v53, 0xffff0000, v70
	v_lshlrev_b32_e32 v54, 16, v71
	v_and_b32_e32 v55, 0xffff0000, v71
	v_pk_add_f32 v[44:45], v[44:45], v[48:49]
	v_lshlrev_b32_e32 v50, 16, v69
	v_and_b32_e32 v51, 0xffff0000, v69
	v_pk_add_f32 v[48:49], v[42:43], v[54:55]
	v_pk_add_f32 v[42:43], v[40:41], v[52:53]
	v_cvt_pk_bf16_f32 v40, v44, v45
	v_lshl_add_u64 v[44:45], s[68:69], 0, v[78:79]
	v_pk_add_f32 v[46:47], v[46:47], v[50:51]
	v_lshl_add_u64 v[44:45], v[168:169], 1, v[44:45]
	v_cvt_pk_bf16_f32 v41, v46, v47
	v_cvt_pk_bf16_f32 v42, v42, v43
	v_cvt_pk_bf16_f32 v43, v48, v49
	global_store_dwordx4 v[44:45], v[40:43], off nt
	v_lshlrev_b32_e32 v46, 16, v40
	v_and_b32_e32 v47, 0xffff0000, v66
	v_and_b32_e32 v40, 0xffff0000, v40
	v_mul_f32_e32 v40, v40, v40
	v_fmac_f32_e32 v40, v46, v46
	v_lshlrev_b32_e32 v46, 16, v41
	v_and_b32_e32 v41, 0xffff0000, v41
	v_mul_f32_e32 v41, v41, v41
	v_fmac_f32_e32 v41, v46, v46
	v_add_f32_e32 v40, v40, v41
	v_lshlrev_b32_e32 v41, 16, v42
	v_and_b32_e32 v42, 0xffff0000, v42
	v_mul_f32_e32 v42, v42, v42
	v_fmac_f32_e32 v42, v41, v41
	v_add_f32_e32 v40, v40, v42
	v_and_b32_e32 v42, 0xffff0000, v43
	v_lshlrev_b32_e32 v41, 16, v43
	v_mul_f32_e32 v42, v42, v42
	v_fmac_f32_e32 v42, v41, v41
	v_add_f32_e32 v50, v40, v42
	v_lshlrev_b32_e32 v40, 16, v64
	v_and_b32_e32 v41, 0xffff0000, v64
	v_lshlrev_b32_e32 v46, 16, v66
	v_lshlrev_b32_e32 v42, 16, v65
	v_and_b32_e32 v43, 0xffff0000, v65
	v_lshlrev_b32_e32 v48, 16, v67
	v_and_b32_e32 v49, 0xffff0000, v67
	v_pk_add_f32 v[36:37], v[36:37], v[40:41]
	v_pk_add_f32 v[32:33], v[32:33], v[46:47]
	v_pk_add_f32 v[38:39], v[38:39], v[42:43]
	v_pk_add_f32 v[40:41], v[34:35], v[48:49]
	v_cvt_pk_bf16_f32 v34, v36, v37
	v_cvt_pk_bf16_f32 v35, v38, v39
	v_cvt_pk_bf16_f32 v36, v32, v33
	s_nop 0
	v_and_b32_e32 v33, 0xffff0000, v34
	v_lshlrev_b32_e32 v32, 16, v34
	v_mul_f32_e32 v33, v33, v33
	v_fmac_f32_e32 v33, v32, v32
	v_and_b32_e32 v38, 0xffff0000, v35
	v_add_f32_e32 v32, v50, v33
	v_lshlrev_b32_e32 v33, 16, v35
	v_mul_f32_e32 v38, v38, v38
	v_fmac_f32_e32 v38, v33, v33
	v_add_f32_e32 v32, v32, v38
	v_and_b32_e32 v38, 0xffff0000, v36
	v_lshlrev_b32_e32 v33, 16, v36
	v_mul_f32_e32 v38, v38, v38
	v_fmac_f32_e32 v38, v33, v33
	v_cvt_pk_bf16_f32 v37, v40, v41
	v_add_f32_e32 v32, v32, v38
	v_and_b32_e32 v38, 0xffff0000, v37
	v_lshlrev_b32_e32 v33, 16, v37
	v_mul_f32_e32 v38, v38, v38
	v_fmac_f32_e32 v38, v33, v33
	v_add_f32_e32 v32, v32, v38
	v_mov_b32_e32 v33, v32
	s_nop 1
	v_permlane16_swap_b32_e32 v33, v32
	global_store_dwordx4 v[44:45], v[34:37], off offset:256 nt
	s_waitcnt lgkmcnt(0)
	v_add_f32_e32 v32, v32, v33
	v_mov_b32_e32 v33, v32
	s_nop 1
	v_permlane32_swap_b32_e32 v33, v32
	s_and_saveexec_b64 s[6:7], vcc
	s_cbranch_execz .LBB0_390
	v_lshlrev_b64 v[34:35], 6, v[76:77]
	v_lshl_add_u64 v[34:35], s[46:47], 0, v[34:35]
	v_lshl_add_u64 v[34:35], s[56:57], 2, v[34:35]
	s_lshl_b32 s38, s8, 2
	v_lshl_add_u64 v[34:35], v[34:35], 0, s[38:39]
	s_waitcnt lgkmcnt(0)
	v_add_f32_e32 v32, v32, v33
	flat_store_dword v[34:35], v32 sc0 sc1
.LBB0_390:
	s_or_b64 exec, exec, s[6:7]
	v_add_u32_e32 v48, 0xa0, v170
	v_ashrrev_i32_e32 v49, 31, v48
	v_lshlrev_b64 v[54:55], 11, v[48:49]
	s_waitcnt lgkmcnt(0)
	v_lshl_add_u64 v[32:33], v[172:173], 0, v[54:55]
	global_load_dwordx4 v[50:53], v[32:33], off
	global_load_dwordx4 v[40:43], v[32:33], off offset:256
	v_add_u32_e32 v44, 0xb0, v170
	v_ashrrev_i32_e32 v45, 31, v44
	v_lshlrev_b64 v[46:47], 11, v[44:45]
	v_lshl_add_u64 v[32:33], v[172:173], 0, v[46:47]
	global_load_dwordx4 v[36:39], v[32:33], off
	s_nop 0
	global_load_dwordx4 v[32:35], v[32:33], off offset:256
	s_waitcnt vmcnt(0)
	v_lshlrev_b32_e32 v56, 16, v50
	v_and_b32_e32 v57, 0xffff0000, v50
	v_lshlrev_b32_e32 v50, 16, v51
	v_and_b32_e32 v51, 0xffff0000, v51
	v_lshlrev_b32_e32 v58, 16, v52
	v_and_b32_e32 v59, 0xffff0000, v52
	v_lshlrev_b32_e32 v52, 16, v53
	v_and_b32_e32 v53, 0xffff0000, v53
	v_pk_add_f32 v[28:29], v[28:29], v[56:57]
	v_pk_add_f32 v[30:31], v[30:31], v[50:51]
	v_pk_add_f32 v[50:51], v[26:27], v[52:53]
	v_pk_add_f32 v[26:27], v[24:25], v[58:59]
	v_cvt_pk_bf16_f32 v24, v28, v29
	v_lshl_add_u64 v[28:29], s[68:69], 0, v[54:55]
	v_lshl_add_u64 v[28:29], v[168:169], 1, v[28:29]
	v_cvt_pk_bf16_f32 v25, v30, v31
	v_cvt_pk_bf16_f32 v26, v26, v27
	v_cvt_pk_bf16_f32 v27, v50, v51
	global_store_dwordx4 v[28:29], v[24:27], off nt
	v_lshlrev_b32_e32 v30, 16, v24
	v_and_b32_e32 v31, 0xffff0000, v42
	v_and_b32_e32 v24, 0xffff0000, v24
	v_mul_f32_e32 v24, v24, v24
	v_fmac_f32_e32 v24, v30, v30
	v_lshlrev_b32_e32 v30, 16, v25
	v_and_b32_e32 v25, 0xffff0000, v25
	v_mul_f32_e32 v25, v25, v25
	v_fmac_f32_e32 v25, v30, v30
	v_add_f32_e32 v24, v24, v25
	v_lshlrev_b32_e32 v25, 16, v26
	v_and_b32_e32 v26, 0xffff0000, v26
	v_mul_f32_e32 v26, v26, v26
	v_fmac_f32_e32 v26, v25, v25
	v_add_f32_e32 v24, v24, v26
	v_and_b32_e32 v26, 0xffff0000, v27
	v_lshlrev_b32_e32 v25, 16, v27
	v_mul_f32_e32 v26, v26, v26
	v_fmac_f32_e32 v26, v25, v25
	v_add_f32_e32 v50, v24, v26
	v_lshlrev_b32_e32 v24, 16, v40
	v_and_b32_e32 v25, 0xffff0000, v40
	v_lshlrev_b32_e32 v26, 16, v41
	v_and_b32_e32 v27, 0xffff0000, v41
	v_lshlrev_b32_e32 v30, 16, v42
	v_lshlrev_b32_e32 v40, 16, v43
	v_and_b32_e32 v41, 0xffff0000, v43
	v_pk_add_f32 v[20:21], v[20:21], v[24:25]
	v_pk_add_f32 v[24:25], v[18:19], v[40:41]
	v_pk_add_f32 v[18:19], v[16:17], v[30:31]
	v_cvt_pk_bf16_f32 v16, v20, v21
	v_pk_add_f32 v[22:23], v[22:23], v[26:27]
	v_lshlrev_b32_e32 v20, 16, v16
	v_cvt_pk_bf16_f32 v17, v22, v23
	v_cvt_pk_bf16_f32 v18, v18, v19
	v_cvt_pk_bf16_f32 v19, v24, v25
	global_store_dwordx4 v[28:29], v[16:19], off offset:256 nt
	s_nop 1
	v_and_b32_e32 v16, 0xffff0000, v16
	v_mul_f32_e32 v16, v16, v16
	v_fmac_f32_e32 v16, v20, v20
	v_lshlrev_b32_e32 v20, 16, v17
	v_and_b32_e32 v17, 0xffff0000, v17
	v_mul_f32_e32 v17, v17, v17
	v_add_f32_e32 v16, v50, v16
	v_fmac_f32_e32 v17, v20, v20
	v_add_f32_e32 v16, v16, v17
	v_lshlrev_b32_e32 v17, 16, v18
	v_and_b32_e32 v18, 0xffff0000, v18
	v_mul_f32_e32 v18, v18, v18
	v_fmac_f32_e32 v18, v17, v17
	v_add_f32_e32 v16, v16, v18
	v_and_b32_e32 v18, 0xffff0000, v19
	v_lshlrev_b32_e32 v17, 16, v19
	v_mul_f32_e32 v18, v18, v18
	v_fmac_f32_e32 v18, v17, v17
	v_add_f32_e32 v16, v16, v18
	v_mov_b32_e32 v17, v16
	s_nop 1
	v_permlane16_swap_b32_e32 v17, v16
	s_waitcnt lgkmcnt(0)
	v_add_f32_e32 v16, v16, v17
	v_mov_b32_e32 v17, v16
	s_nop 1
	v_permlane32_swap_b32_e32 v17, v16
	s_and_saveexec_b64 s[6:7], vcc
	s_cbranch_execz .LBB0_392
	v_lshlrev_b64 v[18:19], 6, v[48:49]
	v_lshl_add_u64 v[18:19], s[46:47], 0, v[18:19]
	v_lshl_add_u64 v[18:19], s[56:57], 2, v[18:19]
	s_lshl_b32 s38, s8, 2
	v_lshl_add_u64 v[18:19], v[18:19], 0, s[38:39]
	s_waitcnt lgkmcnt(0)
	v_add_f32_e32 v16, v16, v17
	flat_store_dword v[18:19], v16 sc0 sc1
.LBB0_392:
	s_or_b64 exec, exec, s[6:7]
	v_lshlrev_b32_e32 v16, 16, v36
	s_waitcnt lgkmcnt(0)
	v_and_b32_e32 v17, 0xffff0000, v36
	v_lshlrev_b32_e32 v20, 16, v38
	v_and_b32_e32 v21, 0xffff0000, v38
	v_lshlrev_b32_e32 v22, 16, v39
	v_and_b32_e32 v23, 0xffff0000, v39
	v_pk_add_f32 v[12:13], v[12:13], v[16:17]
	v_lshlrev_b32_e32 v18, 16, v37
	v_and_b32_e32 v19, 0xffff0000, v37
	v_pk_add_f32 v[16:17], v[10:11], v[22:23]
	v_pk_add_f32 v[10:11], v[8:9], v[20:21]
	v_cvt_pk_bf16_f32 v8, v12, v13
	v_lshl_add_u64 v[12:13], s[68:69], 0, v[46:47]
	v_pk_add_f32 v[14:15], v[14:15], v[18:19]
	v_lshl_add_u64 v[12:13], v[168:169], 1, v[12:13]
	v_cvt_pk_bf16_f32 v9, v14, v15
	v_cvt_pk_bf16_f32 v10, v10, v11
	v_cvt_pk_bf16_f32 v11, v16, v17
	global_store_dwordx4 v[12:13], v[8:11], off nt
	v_lshlrev_b32_e32 v14, 16, v8
	v_and_b32_e32 v15, 0xffff0000, v34
	v_and_b32_e32 v8, 0xffff0000, v8
	v_mul_f32_e32 v8, v8, v8
	v_fmac_f32_e32 v8, v14, v14
	v_lshlrev_b32_e32 v14, 16, v9
	v_and_b32_e32 v9, 0xffff0000, v9
	v_mul_f32_e32 v9, v9, v9
	v_fmac_f32_e32 v9, v14, v14
	v_add_f32_e32 v8, v8, v9
	v_lshlrev_b32_e32 v9, 16, v10
	v_and_b32_e32 v10, 0xffff0000, v10
	v_mul_f32_e32 v10, v10, v10
	v_fmac_f32_e32 v10, v9, v9
	v_add_f32_e32 v8, v8, v10
	v_and_b32_e32 v10, 0xffff0000, v11
	v_lshlrev_b32_e32 v9, 16, v11
	v_mul_f32_e32 v10, v10, v10
	v_fmac_f32_e32 v10, v9, v9
	v_add_f32_e32 v18, v8, v10
	v_lshlrev_b32_e32 v8, 16, v32
	v_and_b32_e32 v9, 0xffff0000, v32
	v_lshlrev_b32_e32 v14, 16, v34
	v_lshlrev_b32_e32 v10, 16, v33
	v_and_b32_e32 v11, 0xffff0000, v33
	v_lshlrev_b32_e32 v16, 16, v35
	v_and_b32_e32 v17, 0xffff0000, v35
	v_pk_add_f32 v[4:5], v[4:5], v[8:9]
	v_pk_add_f32 v[0:1], v[0:1], v[14:15]
	v_pk_add_f32 v[6:7], v[6:7], v[10:11]
	v_pk_add_f32 v[8:9], v[2:3], v[16:17]
	v_cvt_pk_bf16_f32 v2, v4, v5
	v_cvt_pk_bf16_f32 v3, v6, v7
	v_cvt_pk_bf16_f32 v4, v0, v1
	s_nop 0
	v_and_b32_e32 v1, 0xffff0000, v2
	v_lshlrev_b32_e32 v0, 16, v2
	v_mul_f32_e32 v1, v1, v1
	v_fmac_f32_e32 v1, v0, v0
	v_and_b32_e32 v6, 0xffff0000, v3
	v_add_f32_e32 v0, v18, v1
	v_lshlrev_b32_e32 v1, 16, v3
	v_mul_f32_e32 v6, v6, v6
	v_fmac_f32_e32 v6, v1, v1
	v_add_f32_e32 v0, v0, v6
	v_and_b32_e32 v6, 0xffff0000, v4
	v_lshlrev_b32_e32 v1, 16, v4
	v_mul_f32_e32 v6, v6, v6
	v_fmac_f32_e32 v6, v1, v1
	v_cvt_pk_bf16_f32 v5, v8, v9
	v_add_f32_e32 v0, v0, v6
	v_and_b32_e32 v6, 0xffff0000, v5
	v_lshlrev_b32_e32 v1, 16, v5
	v_mul_f32_e32 v6, v6, v6
	v_fmac_f32_e32 v6, v1, v1
	v_add_f32_e32 v0, v0, v6
	v_mov_b32_e32 v1, v0
	s_nop 1
	v_permlane16_swap_b32_e32 v1, v0
	global_store_dwordx4 v[12:13], v[2:5], off offset:256 nt
	s_waitcnt lgkmcnt(0)
	v_add_f32_e32 v0, v0, v1
	v_mov_b32_e32 v1, v0
	s_nop 1
	v_permlane32_swap_b32_e32 v1, v0
	s_and_saveexec_b64 s[6:7], vcc
	s_cbranch_execz .LBB0_394
	v_lshlrev_b64 v[2:3], 6, v[44:45]
	v_lshl_add_u64 v[2:3], s[46:47], 0, v[2:3]
	v_lshl_add_u64 v[2:3], s[56:57], 2, v[2:3]
	s_lshl_b32 s38, s8, 2
	v_lshl_add_u64 v[2:3], v[2:3], 0, s[38:39]
	s_waitcnt lgkmcnt(0)
	v_add_f32_e32 v0, v0, v1
	flat_store_dword v[2:3], v0 sc0 sc1

.LBB0_419:
	s_mov_b32 s6, -1
	s_lshl_b32 s5, s5, 8
	v_mbcnt_lo_u32_b32 v112, s6, 0
	v_mbcnt_hi_u32_b32 v112, s6, v112
	s_getreg_b32 s6, hwreg(HW_REG_HW_ID, 0, 6)
	s_and_b32 s6, s6, 63
	s_lshl_b32 s6, s6, 2
	s_add_i32 s6, s6, 0
	s_add_i32 s6, s6, 0x20200
	v_mov_b32_e32 v113, s6
	ds_read_b32 v113, v113
	v_bfrev_b32_e32 v114, 0.5
	s_movk_i32 s84, 0x80
	s_lshl_b32 s58, s4, 2
	s_ashr_i32 s59, s58, 31
	s_waitcnt lgkmcnt(0)
	v_readfirstlane_b32 s6, v113
	s_nop 1
	v_lshl_add_u32 v112, s6, 6, v112
	s_nop 0
	v_readfirstlane_b32 s6, v112
	s_bfe_u32 s8, s6, 0x20006
	s_ashr_i32 s6, s6, 2
	s_andn2_b32 s6, s6, 63
	s_add_i32 s6, s6, s5
	v_and_or_b32 v166, v112, 15, s6
	s_lshl_b32 s5, s4, 8
	s_lshl_b32 s6, s8, 5
	v_bfe_u32 v113, v112, 4, 2
	s_or_b32 s5, s6, s5
	v_lshl_or_b32 v164, v113, 3, s5
	v_ashrrev_i32_e32 v165, 31, v164
	v_lshlrev_b64 v[146:147], 1, v[164:165]
	v_ashrrev_i32_e32 v167, 31, v166
	v_lshlrev_b32_e32 v112, 2, v112
	v_lshl_add_u64 v[168:169], s[68:69], 0, v[146:147]
	v_lshlrev_b64 v[148:149], 11, v[166:167]
	v_bitop3_b32 v176, v112, 64, v114 bitop3:0x6c
	v_bitop3_b32 v177, v112, s84, v114 bitop3:0x6c
	v_cmp_eq_u32_e32 vcc, 0, v113
	v_lshl_add_u64 v[112:113], v[168:169], 0, v[148:149]
	global_load_dwordx4 v[142:145], v[112:113], off
	global_load_dwordx4 v[128:131], v[112:113], off offset:256
	v_or_b32_e32 v170, 16, v166
	v_ashrrev_i32_e32 v171, 31, v170
	v_lshlrev_b64 v[172:173], 11, v[170:171]
	v_lshl_add_u64 v[112:113], v[168:169], 0, v[172:173]
	global_load_dwordx4 v[116:119], v[112:113], off
	s_nop 0
	global_load_dwordx4 v[112:115], v[112:113], off offset:256
	s_waitcnt vmcnt(0)
	v_lshlrev_b32_e32 v150, 16, v142
	v_and_b32_e32 v151, 0xffff0000, v142
	v_lshlrev_b32_e32 v142, 16, v143
	v_and_b32_e32 v143, 0xffff0000, v143
	v_lshlrev_b32_e32 v152, 16, v144
	v_and_b32_e32 v153, 0xffff0000, v144
	v_pk_add_f32 v[134:135], v[134:135], v[142:143]
	v_pk_add_f32 v[132:133], v[132:133], v[150:151]
	v_pk_add_f32 v[136:137], v[136:137], v[152:153]
	v_lshlrev_b32_e32 v144, 16, v145
	v_and_b32_e32 v145, 0xffff0000, v145
	v_cvt_pk_bf16_f32 v132, v132, v133
	v_cvt_pk_bf16_f32 v133, v134, v135
	v_cvt_pk_bf16_f32 v134, v136, v137
	v_lshl_add_u64 v[136:137], s[68:69], 0, v[148:149]
	v_pk_add_f32 v[138:139], v[138:139], v[144:145]
	v_lshl_add_u64 v[136:137], v[136:137], 0, v[146:147]
	v_cvt_pk_bf16_f32 v135, v138, v139
	global_store_dwordx4 v[136:137], v[132:135], off nt
	v_lshlrev_b32_e32 v138, 16, v132
	s_nop 0
	v_and_b32_e32 v132, 0xffff0000, v132
	v_mul_f32_e32 v132, v132, v132
	v_fmac_f32_e32 v132, v138, v138
	v_lshlrev_b32_e32 v138, 16, v133
	v_and_b32_e32 v133, 0xffff0000, v133
	v_mul_f32_e32 v133, v133, v133
	v_fmac_f32_e32 v133, v138, v138
	v_add_f32_e32 v132, v132, v133
	v_lshlrev_b32_e32 v133, 16, v134
	v_and_b32_e32 v134, 0xffff0000, v134
	v_mul_f32_e32 v134, v134, v134
	v_fmac_f32_e32 v134, v133, v133
	v_add_f32_e32 v132, v132, v134
	v_and_b32_e32 v134, 0xffff0000, v135
	v_lshlrev_b32_e32 v133, 16, v135
	v_mul_f32_e32 v134, v134, v134
	v_fmac_f32_e32 v134, v133, v133
	v_add_f32_e32 v138, v132, v134
	v_lshlrev_b32_e32 v132, 16, v128
	v_and_b32_e32 v133, 0xffff0000, v128
	v_lshlrev_b32_e32 v128, 16, v129
	v_and_b32_e32 v129, 0xffff0000, v129
	v_lshlrev_b32_e32 v134, 16, v130
	v_and_b32_e32 v135, 0xffff0000, v130
	v_lshlrev_b32_e32 v130, 16, v131
	v_and_b32_e32 v131, 0xffff0000, v131
	v_pk_add_f32 v[126:127], v[126:127], v[128:129]
	v_pk_add_f32 v[124:125], v[124:125], v[132:133]
	v_pk_add_f32 v[128:129], v[122:123], v[130:131]
	v_pk_add_f32 v[122:123], v[120:121], v[134:135]
	v_cvt_pk_bf16_f32 v120, v124, v125
	v_cvt_pk_bf16_f32 v121, v126, v127
	s_nop 0
	v_cvt_pk_bf16_f32 v122, v122, v123
	v_cvt_pk_bf16_f32 v123, v128, v129
	global_store_dwordx4 v[136:137], v[120:123], off offset:256 nt
	v_lshlrev_b32_e32 v124, 16, v120
	s_nop 0
	v_and_b32_e32 v120, 0xffff0000, v120
	v_mul_f32_e32 v120, v120, v120
	v_fmac_f32_e32 v120, v124, v124
	v_lshlrev_b32_e32 v124, 16, v121
	v_and_b32_e32 v121, 0xffff0000, v121
	v_mul_f32_e32 v121, v121, v121
	v_add_f32_e32 v120, v138, v120
	v_fmac_f32_e32 v121, v124, v124
	v_add_f32_e32 v120, v120, v121
	v_lshlrev_b32_e32 v121, 16, v122
	v_and_b32_e32 v122, 0xffff0000, v122
	v_mul_f32_e32 v122, v122, v122
	v_fmac_f32_e32 v122, v121, v121
	v_add_f32_e32 v120, v120, v122
	v_and_b32_e32 v122, 0xffff0000, v123
	v_lshlrev_b32_e32 v121, 16, v123
	v_mul_f32_e32 v122, v122, v122
	v_fmac_f32_e32 v122, v121, v121
	v_add_f32_e32 v120, v120, v122
	v_mov_b32_e32 v121, v120
	s_nop 1
	v_permlane16_swap_b32_e32 v121, v120
	s_waitcnt lgkmcnt(0)
	v_add_f32_e32 v120, v120, v121
	v_mov_b32_e32 v121, v120
	s_nop 1
	v_permlane32_swap_b32_e32 v121, v120
	s_and_saveexec_b64 s[6:7], vcc
	s_cbranch_execz .LBB0_421
	s_waitcnt lgkmcnt(0)
	v_add_f32_e32 v122, v120, v121
	v_lshlrev_b64 v[120:121], 6, v[166:167]
	v_lshl_add_u64 v[120:121], s[46:47], 0, v[120:121]
	v_lshl_add_u64 v[120:121], s[58:59], 2, v[120:121]
	s_lshl_b32 s38, s8, 2
	v_lshl_add_u64 v[120:121], v[120:121], 0, s[38:39]
	flat_store_dword v[120:121], v122 sc0 sc1
.LBB0_421:
	s_or_b64 exec, exec, s[6:7]
	v_lshlrev_b32_e32 v120, 16, v116
	s_waitcnt lgkmcnt(0)
	v_and_b32_e32 v121, 0xffff0000, v116
	v_lshlrev_b32_e32 v116, 16, v117
	v_and_b32_e32 v117, 0xffff0000, v117
	v_lshlrev_b32_e32 v122, 16, v118
	v_and_b32_e32 v123, 0xffff0000, v118
	v_lshlrev_b32_e32 v118, 16, v119
	v_and_b32_e32 v119, 0xffff0000, v119
	v_pk_add_f32 v[108:109], v[108:109], v[120:121]
	v_pk_add_f32 v[110:111], v[110:111], v[116:117]
	v_pk_add_f32 v[116:117], v[106:107], v[118:119]
	v_pk_add_f32 v[106:107], v[104:105], v[122:123]
	v_cvt_pk_bf16_f32 v104, v108, v109
	v_lshl_add_u64 v[108:109], s[68:69], 0, v[172:173]
	v_lshl_add_u64 v[108:109], v[164:165], 1, v[108:109]
	v_cvt_pk_bf16_f32 v105, v110, v111
	v_cvt_pk_bf16_f32 v106, v106, v107
	v_cvt_pk_bf16_f32 v107, v116, v117
	global_store_dwordx4 v[108:109], v[104:107], off nt
	v_lshlrev_b32_e32 v110, 16, v104
	v_and_b32_e32 v111, 0xffff0000, v114
	v_and_b32_e32 v104, 0xffff0000, v104
	v_mul_f32_e32 v104, v104, v104
	v_fmac_f32_e32 v104, v110, v110
	v_lshlrev_b32_e32 v110, 16, v105
	v_and_b32_e32 v105, 0xffff0000, v105
	v_mul_f32_e32 v105, v105, v105
	v_fmac_f32_e32 v105, v110, v110
	v_add_f32_e32 v104, v104, v105
	v_lshlrev_b32_e32 v105, 16, v106
	v_and_b32_e32 v106, 0xffff0000, v106
	v_mul_f32_e32 v106, v106, v106
	v_fmac_f32_e32 v106, v105, v105
	v_add_f32_e32 v104, v104, v106
	v_and_b32_e32 v106, 0xffff0000, v107
	v_lshlrev_b32_e32 v105, 16, v107
	v_mul_f32_e32 v106, v106, v106
	v_fmac_f32_e32 v106, v105, v105
	v_add_f32_e32 v116, v104, v106
	v_lshlrev_b32_e32 v104, 16, v112
	v_and_b32_e32 v105, 0xffff0000, v112
	v_lshlrev_b32_e32 v110, 16, v114
	v_lshlrev_b32_e32 v106, 16, v113
	v_and_b32_e32 v107, 0xffff0000, v113
	v_lshlrev_b32_e32 v112, 16, v115
	v_and_b32_e32 v113, 0xffff0000, v115
	v_pk_add_f32 v[100:101], v[100:101], v[104:105]
	v_pk_add_f32 v[96:97], v[96:97], v[110:111]
	v_pk_add_f32 v[102:103], v[102:103], v[106:107]
	v_pk_add_f32 v[104:105], v[98:99], v[112:113]
	v_cvt_pk_bf16_f32 v98, v100, v101
	v_cvt_pk_bf16_f32 v99, v102, v103
	v_cvt_pk_bf16_f32 v100, v96, v97
	s_nop 0
	v_and_b32_e32 v97, 0xffff0000, v98
	v_lshlrev_b32_e32 v96, 16, v98
	v_mul_f32_e32 v97, v97, v97
	v_fmac_f32_e32 v97, v96, v96
	v_and_b32_e32 v102, 0xffff0000, v99
	v_add_f32_e32 v96, v116, v97
	v_lshlrev_b32_e32 v97, 16, v99
	v_mul_f32_e32 v102, v102, v102
	v_fmac_f32_e32 v102, v97, v97
	v_add_f32_e32 v96, v96, v102
	v_and_b32_e32 v102, 0xffff0000, v100
	v_lshlrev_b32_e32 v97, 16, v100
	v_mul_f32_e32 v102, v102, v102
	v_fmac_f32_e32 v102, v97, v97
	v_cvt_pk_bf16_f32 v101, v104, v105
	v_add_f32_e32 v96, v96, v102
	v_and_b32_e32 v102, 0xffff0000, v101
	v_lshlrev_b32_e32 v97, 16, v101
	v_mul_f32_e32 v102, v102, v102
	v_fmac_f32_e32 v102, v97, v97
	v_add_f32_e32 v96, v96, v102
	v_mov_b32_e32 v97, v96
	s_nop 1
	v_permlane16_swap_b32_e32 v97, v96
	global_store_dwordx4 v[108:109], v[98:101], off offset:256 nt
	s_waitcnt lgkmcnt(0)
	v_add_f32_e32 v96, v96, v97
	v_mov_b32_e32 v97, v96
	s_nop 1
	v_permlane32_swap_b32_e32 v97, v96
	s_mov_b64 s[6:7], exec
	s_and_b64 s[4:5], s[6:7], vcc
	v_mov_b32_e32 v198, v246
	v_mov_b32_e32 v199, v247
	v_mov_b32_e32 v205, v249
	v_mov_b32_e32 v196, v251
	v_mov_b32_e32 v251, 0x260
	s_mov_b64 exec, s[4:5]
	s_cbranch_execz .LBB0_423
	s_waitcnt lgkmcnt(0)
	v_add_f32_e32 v98, v96, v97
	v_lshlrev_b64 v[96:97], 6, v[170:171]
	v_lshl_add_u64 v[96:97], s[46:47], 0, v[96:97]
	v_lshl_add_u64 v[96:97], s[58:59], 2, v[96:97]
	s_lshl_b32 s38, s8, 2
	v_lshl_add_u64 v[96:97], v[96:97], 0, s[38:39]
	flat_store_dword v[96:97], v98 sc0 sc1
.LBB0_423:
	s_or_b64 exec, exec, s[6:7]
	v_or_b32_e32 v112, 32, v166
	v_ashrrev_i32_e32 v113, 31, v112
	v_lshlrev_b64 v[118:119], 11, v[112:113]
	s_waitcnt lgkmcnt(0)
	v_lshl_add_u64 v[96:97], v[168:169], 0, v[118:119]
	global_load_dwordx4 v[114:117], v[96:97], off
	global_load_dwordx4 v[104:107], v[96:97], off offset:256
	v_or_b32_e32 v108, 48, v166
	v_ashrrev_i32_e32 v109, 31, v108
	v_lshlrev_b64 v[110:111], 11, v[108:109]
	v_lshl_add_u64 v[96:97], v[168:169], 0, v[110:111]
	global_load_dwordx4 v[100:103], v[96:97], off
	s_nop 0
	global_load_dwordx4 v[96:99], v[96:97], off offset:256
	s_waitcnt vmcnt(0)
	v_lshlrev_b32_e32 v120, 16, v114
	v_and_b32_e32 v121, 0xffff0000, v114
	v_lshlrev_b32_e32 v114, 16, v115
	v_and_b32_e32 v115, 0xffff0000, v115
	v_lshlrev_b32_e32 v122, 16, v116
	v_and_b32_e32 v123, 0xffff0000, v116
	v_pk_add_f32 v[90:91], v[90:91], v[114:115]
	v_pk_add_f32 v[88:89], v[88:89], v[120:121]
	v_pk_add_f32 v[92:93], v[92:93], v[122:123]
	v_lshlrev_b32_e32 v116, 16, v117
	v_and_b32_e32 v117, 0xffff0000, v117
	v_cvt_pk_bf16_f32 v88, v88, v89
	v_cvt_pk_bf16_f32 v89, v90, v91
	v_cvt_pk_bf16_f32 v90, v92, v93
	v_lshl_add_u64 v[92:93], s[68:69], 0, v[118:119]
	v_pk_add_f32 v[94:95], v[94:95], v[116:117]
	v_lshl_add_u64 v[92:93], v[164:165], 1, v[92:93]
	v_cvt_pk_bf16_f32 v91, v94, v95
	global_store_dwordx4 v[92:93], v[88:91], off nt
	v_lshlrev_b32_e32 v94, 16, v88
	v_and_b32_e32 v95, 0xffff0000, v106
	v_and_b32_e32 v88, 0xffff0000, v88
	v_mul_f32_e32 v88, v88, v88
	v_fmac_f32_e32 v88, v94, v94
	v_lshlrev_b32_e32 v94, 16, v89
	v_and_b32_e32 v89, 0xffff0000, v89
	v_mul_f32_e32 v89, v89, v89
	v_fmac_f32_e32 v89, v94, v94
	v_add_f32_e32 v88, v88, v89
	v_lshlrev_b32_e32 v89, 16, v90
	v_and_b32_e32 v90, 0xffff0000, v90
	v_mul_f32_e32 v90, v90, v90
	v_fmac_f32_e32 v90, v89, v89
	v_add_f32_e32 v88, v88, v90
	v_and_b32_e32 v90, 0xffff0000, v91
	v_lshlrev_b32_e32 v89, 16, v91
	v_mul_f32_e32 v90, v90, v90
	v_fmac_f32_e32 v90, v89, v89
	v_add_f32_e32 v114, v88, v90
	v_lshlrev_b32_e32 v88, 16, v104
	v_and_b32_e32 v89, 0xffff0000, v104
	v_lshlrev_b32_e32 v90, 16, v105
	v_and_b32_e32 v91, 0xffff0000, v105
	v_lshlrev_b32_e32 v94, 16, v106
	v_lshlrev_b32_e32 v104, 16, v107
	v_and_b32_e32 v105, 0xffff0000, v107
	v_pk_add_f32 v[84:85], v[84:85], v[88:89]
	v_pk_add_f32 v[88:89], v[82:83], v[104:105]
	v_pk_add_f32 v[82:83], v[80:81], v[94:95]
	v_cvt_pk_bf16_f32 v80, v84, v85
	v_pk_add_f32 v[86:87], v[86:87], v[90:91]
	v_lshlrev_b32_e32 v84, 16, v80
	v_cvt_pk_bf16_f32 v81, v86, v87
	v_cvt_pk_bf16_f32 v82, v82, v83
	v_cvt_pk_bf16_f32 v83, v88, v89
	global_store_dwordx4 v[92:93], v[80:83], off offset:256 nt
	s_nop 1
	v_and_b32_e32 v80, 0xffff0000, v80
	v_mul_f32_e32 v80, v80, v80
	v_fmac_f32_e32 v80, v84, v84
	v_lshlrev_b32_e32 v84, 16, v81
	v_and_b32_e32 v81, 0xffff0000, v81
	v_mul_f32_e32 v81, v81, v81
	v_add_f32_e32 v80, v114, v80
	v_fmac_f32_e32 v81, v84, v84
	v_add_f32_e32 v80, v80, v81
	v_lshlrev_b32_e32 v81, 16, v82
	v_and_b32_e32 v82, 0xffff0000, v82
	v_mul_f32_e32 v82, v82, v82
	v_fmac_f32_e32 v82, v81, v81
	v_add_f32_e32 v80, v80, v82
	v_and_b32_e32 v82, 0xffff0000, v83
	v_lshlrev_b32_e32 v81, 16, v83
	v_mul_f32_e32 v82, v82, v82
	v_fmac_f32_e32 v82, v81, v81
	v_add_f32_e32 v80, v80, v82
	v_mov_b32_e32 v81, v80
	s_nop 1
	v_permlane16_swap_b32_e32 v81, v80
	s_waitcnt lgkmcnt(0)
	v_add_f32_e32 v80, v80, v81
	v_mov_b32_e32 v81, v80
	s_nop 1
	v_permlane32_swap_b32_e32 v81, v80
	s_and_saveexec_b64 s[6:7], vcc
	s_cbranch_execz .LBB0_425
	s_waitcnt lgkmcnt(0)
	v_add_f32_e32 v82, v80, v81
	v_lshlrev_b64 v[80:81], 6, v[112:113]
	v_lshl_add_u64 v[80:81], s[46:47], 0, v[80:81]
	v_lshl_add_u64 v[80:81], s[58:59], 2, v[80:81]
	s_lshl_b32 s38, s8, 2
	v_lshl_add_u64 v[80:81], v[80:81], 0, s[38:39]
	flat_store_dword v[80:81], v82 sc0 sc1
.LBB0_425:
	s_or_b64 exec, exec, s[6:7]
	v_lshlrev_b32_e32 v80, 16, v100
	s_waitcnt lgkmcnt(0)
	v_and_b32_e32 v81, 0xffff0000, v100
	v_lshlrev_b32_e32 v84, 16, v102
	v_and_b32_e32 v85, 0xffff0000, v102
	v_lshlrev_b32_e32 v86, 16, v103
	v_and_b32_e32 v87, 0xffff0000, v103
	v_pk_add_f32 v[76:77], v[76:77], v[80:81]
	v_lshlrev_b32_e32 v82, 16, v101
	v_and_b32_e32 v83, 0xffff0000, v101
	v_pk_add_f32 v[80:81], v[74:75], v[86:87]
	v_pk_add_f32 v[74:75], v[72:73], v[84:85]
	v_cvt_pk_bf16_f32 v72, v76, v77
	v_lshl_add_u64 v[76:77], s[68:69], 0, v[110:111]
	v_pk_add_f32 v[78:79], v[78:79], v[82:83]
	v_lshl_add_u64 v[76:77], v[164:165], 1, v[76:77]
	v_cvt_pk_bf16_f32 v73, v78, v79
	v_cvt_pk_bf16_f32 v74, v74, v75
	v_cvt_pk_bf16_f32 v75, v80, v81
	global_store_dwordx4 v[76:77], v[72:75], off nt
	v_lshlrev_b32_e32 v78, 16, v72
	v_and_b32_e32 v79, 0xffff0000, v98
	v_and_b32_e32 v72, 0xffff0000, v72
	v_mul_f32_e32 v72, v72, v72
	v_fmac_f32_e32 v72, v78, v78
	v_lshlrev_b32_e32 v78, 16, v73
	v_and_b32_e32 v73, 0xffff0000, v73
	v_mul_f32_e32 v73, v73, v73
	v_fmac_f32_e32 v73, v78, v78
	v_add_f32_e32 v72, v72, v73
	v_lshlrev_b32_e32 v73, 16, v74
	v_and_b32_e32 v74, 0xffff0000, v74
	v_mul_f32_e32 v74, v74, v74
	v_fmac_f32_e32 v74, v73, v73
	v_add_f32_e32 v72, v72, v74
	v_and_b32_e32 v74, 0xffff0000, v75
	v_lshlrev_b32_e32 v73, 16, v75
	v_mul_f32_e32 v74, v74, v74
	v_fmac_f32_e32 v74, v73, v73
	v_add_f32_e32 v82, v72, v74
	v_lshlrev_b32_e32 v72, 16, v96
	v_and_b32_e32 v73, 0xffff0000, v96
	v_lshlrev_b32_e32 v78, 16, v98
	v_lshlrev_b32_e32 v74, 16, v97
	v_and_b32_e32 v75, 0xffff0000, v97
	v_lshlrev_b32_e32 v80, 16, v99
	v_and_b32_e32 v81, 0xffff0000, v99
	v_pk_add_f32 v[68:69], v[68:69], v[72:73]
	v_pk_add_f32 v[64:65], v[64:65], v[78:79]
	v_pk_add_f32 v[70:71], v[70:71], v[74:75]
	v_pk_add_f32 v[72:73], v[66:67], v[80:81]
	v_cvt_pk_bf16_f32 v66, v68, v69
	v_cvt_pk_bf16_f32 v67, v70, v71
	v_cvt_pk_bf16_f32 v68, v64, v65
	s_nop 0
	v_and_b32_e32 v65, 0xffff0000, v66
	v_lshlrev_b32_e32 v64, 16, v66
	v_mul_f32_e32 v65, v65, v65
	v_fmac_f32_e32 v65, v64, v64
	v_and_b32_e32 v70, 0xffff0000, v67
	v_add_f32_e32 v64, v82, v65
	v_lshlrev_b32_e32 v65, 16, v67
	v_mul_f32_e32 v70, v70, v70
	v_fmac_f32_e32 v70, v65, v65
	v_add_f32_e32 v64, v64, v70
	v_and_b32_e32 v70, 0xffff0000, v68
	v_lshlrev_b32_e32 v65, 16, v68
	v_mul_f32_e32 v70, v70, v70
	v_fmac_f32_e32 v70, v65, v65
	v_cvt_pk_bf16_f32 v69, v72, v73
	v_add_f32_e32 v64, v64, v70
	v_and_b32_e32 v70, 0xffff0000, v69
	v_lshlrev_b32_e32 v65, 16, v69
	v_mul_f32_e32 v70, v70, v70
	v_fmac_f32_e32 v70, v65, v65
	v_add_f32_e32 v64, v64, v70
	v_mov_b32_e32 v65, v64
	s_nop 1
	v_permlane16_swap_b32_e32 v65, v64
	global_store_dwordx4 v[76:77], v[66:69], off offset:256 nt
	s_waitcnt lgkmcnt(0)
	v_add_f32_e32 v64, v64, v65
	v_mov_b32_e32 v65, v64
	s_nop 1
	v_permlane32_swap_b32_e32 v65, v64
	s_and_saveexec_b64 s[6:7], vcc
	s_cbranch_execz .LBB0_427
	s_waitcnt lgkmcnt(0)
	v_add_f32_e32 v66, v64, v65
	v_lshlrev_b64 v[64:65], 6, v[108:109]
	v_lshl_add_u64 v[64:65], s[46:47], 0, v[64:65]
	v_lshl_add_u64 v[64:65], s[58:59], 2, v[64:65]
	s_lshl_b32 s38, s8, 2
	v_lshl_add_u64 v[64:65], v[64:65], 0, s[38:39]
	flat_store_dword v[64:65], v66 sc0 sc1
.LBB0_427:
	s_or_b64 exec, exec, s[6:7]
	v_add_u32_e32 v80, 0x80, v166
	v_ashrrev_i32_e32 v81, 31, v80
	v_lshlrev_b64 v[86:87], 11, v[80:81]
	s_waitcnt lgkmcnt(0)
	v_lshl_add_u64 v[64:65], v[168:169], 0, v[86:87]
	global_load_dwordx4 v[82:85], v[64:65], off
	global_load_dwordx4 v[72:75], v[64:65], off offset:256
	v_add_u32_e32 v76, 0x90, v166
	v_ashrrev_i32_e32 v77, 31, v76
	v_lshlrev_b64 v[78:79], 11, v[76:77]
	v_lshl_add_u64 v[64:65], v[168:169], 0, v[78:79]
	global_load_dwordx4 v[68:71], v[64:65], off
	s_nop 0
	global_load_dwordx4 v[64:67], v[64:65], off offset:256
	s_waitcnt vmcnt(0)
	v_lshlrev_b32_e32 v88, 16, v82
	v_and_b32_e32 v89, 0xffff0000, v82
	v_lshlrev_b32_e32 v82, 16, v83
	v_and_b32_e32 v83, 0xffff0000, v83
	v_lshlrev_b32_e32 v90, 16, v84
	v_and_b32_e32 v91, 0xffff0000, v84
	v_pk_add_f32 v[58:59], v[58:59], v[82:83]
	v_pk_add_f32 v[56:57], v[56:57], v[88:89]
	v_pk_add_f32 v[60:61], v[60:61], v[90:91]
	v_lshlrev_b32_e32 v84, 16, v85
	v_and_b32_e32 v85, 0xffff0000, v85
	v_cvt_pk_bf16_f32 v56, v56, v57
	v_cvt_pk_bf16_f32 v57, v58, v59
	v_cvt_pk_bf16_f32 v58, v60, v61
	v_lshl_add_u64 v[60:61], s[68:69], 0, v[86:87]
	v_pk_add_f32 v[62:63], v[62:63], v[84:85]
	v_lshl_add_u64 v[60:61], v[164:165], 1, v[60:61]
	v_cvt_pk_bf16_f32 v59, v62, v63
	global_store_dwordx4 v[60:61], v[56:59], off nt
	v_lshlrev_b32_e32 v62, 16, v56
	v_and_b32_e32 v63, 0xffff0000, v74
	v_and_b32_e32 v56, 0xffff0000, v56
	v_mul_f32_e32 v56, v56, v56
	v_fmac_f32_e32 v56, v62, v62
	v_lshlrev_b32_e32 v62, 16, v57
	v_and_b32_e32 v57, 0xffff0000, v57
	v_mul_f32_e32 v57, v57, v57
	v_fmac_f32_e32 v57, v62, v62
	v_add_f32_e32 v56, v56, v57
	v_lshlrev_b32_e32 v57, 16, v58
	v_and_b32_e32 v58, 0xffff0000, v58
	v_mul_f32_e32 v58, v58, v58
	v_fmac_f32_e32 v58, v57, v57
	v_add_f32_e32 v56, v56, v58
	v_and_b32_e32 v58, 0xffff0000, v59
	v_lshlrev_b32_e32 v57, 16, v59
	v_mul_f32_e32 v58, v58, v58
	v_fmac_f32_e32 v58, v57, v57
	v_add_f32_e32 v82, v56, v58
	v_lshlrev_b32_e32 v56, 16, v72
	v_and_b32_e32 v57, 0xffff0000, v72
	v_lshlrev_b32_e32 v58, 16, v73
	v_and_b32_e32 v59, 0xffff0000, v73
	v_lshlrev_b32_e32 v62, 16, v74
	v_lshlrev_b32_e32 v72, 16, v75
	v_and_b32_e32 v73, 0xffff0000, v75
	v_pk_add_f32 v[52:53], v[52:53], v[56:57]
	v_pk_add_f32 v[56:57], v[50:51], v[72:73]
	v_pk_add_f32 v[50:51], v[48:49], v[62:63]
	v_cvt_pk_bf16_f32 v48, v52, v53
	v_pk_add_f32 v[54:55], v[54:55], v[58:59]
	v_lshlrev_b32_e32 v52, 16, v48
	v_cvt_pk_bf16_f32 v49, v54, v55
	v_cvt_pk_bf16_f32 v50, v50, v51
	v_cvt_pk_bf16_f32 v51, v56, v57
	global_store_dwordx4 v[60:61], v[48:51], off offset:256 nt
	s_nop 1
	v_and_b32_e32 v48, 0xffff0000, v48
	v_mul_f32_e32 v48, v48, v48
	v_fmac_f32_e32 v48, v52, v52
	v_lshlrev_b32_e32 v52, 16, v49
	v_and_b32_e32 v49, 0xffff0000, v49
	v_mul_f32_e32 v49, v49, v49
	v_add_f32_e32 v48, v82, v48
	v_fmac_f32_e32 v49, v52, v52
	v_add_f32_e32 v48, v48, v49
	v_lshlrev_b32_e32 v49, 16, v50
	v_and_b32_e32 v50, 0xffff0000, v50
	v_mul_f32_e32 v50, v50, v50
	v_fmac_f32_e32 v50, v49, v49
	v_add_f32_e32 v48, v48, v50
	v_and_b32_e32 v50, 0xffff0000, v51
	v_lshlrev_b32_e32 v49, 16, v51
	v_mul_f32_e32 v50, v50, v50
	v_fmac_f32_e32 v50, v49, v49
	v_add_f32_e32 v48, v48, v50
	v_mov_b32_e32 v49, v48
	s_nop 1
	v_permlane16_swap_b32_e32 v49, v48
	s_waitcnt lgkmcnt(0)
	v_add_f32_e32 v48, v48, v49
	v_mov_b32_e32 v49, v48
	s_nop 1
	v_permlane32_swap_b32_e32 v49, v48
	s_and_saveexec_b64 s[6:7], vcc
	s_cbranch_execz .LBB0_429
	s_waitcnt lgkmcnt(0)
	v_add_f32_e32 v50, v48, v49
	v_lshlrev_b64 v[48:49], 6, v[80:81]
	v_lshl_add_u64 v[48:49], s[46:47], 0, v[48:49]
	v_lshl_add_u64 v[48:49], s[58:59], 2, v[48:49]
	s_lshl_b32 s38, s8, 2
	v_lshl_add_u64 v[48:49], v[48:49], 0, s[38:39]
	flat_store_dword v[48:49], v50 sc0 sc1
.LBB0_429:
	s_or_b64 exec, exec, s[6:7]
	v_lshlrev_b32_e32 v48, 16, v68
	s_waitcnt lgkmcnt(0)
	v_and_b32_e32 v49, 0xffff0000, v68
	v_lshlrev_b32_e32 v52, 16, v70
	v_and_b32_e32 v53, 0xffff0000, v70
	v_lshlrev_b32_e32 v54, 16, v71
	v_and_b32_e32 v55, 0xffff0000, v71
	v_pk_add_f32 v[44:45], v[44:45], v[48:49]
	v_lshlrev_b32_e32 v50, 16, v69
	v_and_b32_e32 v51, 0xffff0000, v69
	v_pk_add_f32 v[48:49], v[42:43], v[54:55]
	v_pk_add_f32 v[42:43], v[40:41], v[52:53]
	v_cvt_pk_bf16_f32 v40, v44, v45
	v_lshl_add_u64 v[44:45], s[68:69], 0, v[78:79]
	v_pk_add_f32 v[46:47], v[46:47], v[50:51]
	v_lshl_add_u64 v[44:45], v[164:165], 1, v[44:45]
	v_cvt_pk_bf16_f32 v41, v46, v47
	v_cvt_pk_bf16_f32 v42, v42, v43
	v_cvt_pk_bf16_f32 v43, v48, v49
	global_store_dwordx4 v[44:45], v[40:43], off nt
	v_lshlrev_b32_e32 v46, 16, v40
	v_and_b32_e32 v47, 0xffff0000, v66
	v_and_b32_e32 v40, 0xffff0000, v40
	v_mul_f32_e32 v40, v40, v40
	v_fmac_f32_e32 v40, v46, v46
	v_lshlrev_b32_e32 v46, 16, v41
	v_and_b32_e32 v41, 0xffff0000, v41
	v_mul_f32_e32 v41, v41, v41
	v_fmac_f32_e32 v41, v46, v46
	v_add_f32_e32 v40, v40, v41
	v_lshlrev_b32_e32 v41, 16, v42
	v_and_b32_e32 v42, 0xffff0000, v42
	v_mul_f32_e32 v42, v42, v42
	v_fmac_f32_e32 v42, v41, v41
	v_add_f32_e32 v40, v40, v42
	v_and_b32_e32 v42, 0xffff0000, v43
	v_lshlrev_b32_e32 v41, 16, v43
	v_mul_f32_e32 v42, v42, v42
	v_fmac_f32_e32 v42, v41, v41
	v_add_f32_e32 v50, v40, v42
	v_lshlrev_b32_e32 v40, 16, v64
	v_and_b32_e32 v41, 0xffff0000, v64
	v_lshlrev_b32_e32 v46, 16, v66
	v_lshlrev_b32_e32 v42, 16, v65
	v_and_b32_e32 v43, 0xffff0000, v65
	v_lshlrev_b32_e32 v48, 16, v67
	v_and_b32_e32 v49, 0xffff0000, v67
	v_pk_add_f32 v[36:37], v[36:37], v[40:41]
	v_pk_add_f32 v[32:33], v[32:33], v[46:47]
	v_pk_add_f32 v[38:39], v[38:39], v[42:43]
	v_pk_add_f32 v[40:41], v[34:35], v[48:49]
	v_cvt_pk_bf16_f32 v34, v36, v37
	v_cvt_pk_bf16_f32 v35, v38, v39
	v_cvt_pk_bf16_f32 v36, v32, v33
	s_nop 0
	v_and_b32_e32 v33, 0xffff0000, v34
	v_lshlrev_b32_e32 v32, 16, v34
	v_mul_f32_e32 v33, v33, v33
	v_fmac_f32_e32 v33, v32, v32
	v_and_b32_e32 v38, 0xffff0000, v35
	v_add_f32_e32 v32, v50, v33
	v_lshlrev_b32_e32 v33, 16, v35
	v_mul_f32_e32 v38, v38, v38
	v_fmac_f32_e32 v38, v33, v33
	v_add_f32_e32 v32, v32, v38
	v_and_b32_e32 v38, 0xffff0000, v36
	v_lshlrev_b32_e32 v33, 16, v36
	v_mul_f32_e32 v38, v38, v38
	v_fmac_f32_e32 v38, v33, v33
	v_cvt_pk_bf16_f32 v37, v40, v41
	v_add_f32_e32 v32, v32, v38
	v_and_b32_e32 v38, 0xffff0000, v37
	v_lshlrev_b32_e32 v33, 16, v37
	v_mul_f32_e32 v38, v38, v38
	v_fmac_f32_e32 v38, v33, v33
	v_add_f32_e32 v32, v32, v38
	v_mov_b32_e32 v33, v32
	s_nop 1
	v_permlane16_swap_b32_e32 v33, v32
	global_store_dwordx4 v[44:45], v[34:37], off offset:256 nt
	s_waitcnt lgkmcnt(0)
	v_add_f32_e32 v32, v32, v33
	v_mov_b32_e32 v33, v32
	s_nop 1
	v_permlane32_swap_b32_e32 v33, v32
	s_and_saveexec_b64 s[6:7], vcc
	s_cbranch_execz .LBB0_431
	s_waitcnt lgkmcnt(0)
	v_add_f32_e32 v34, v32, v33
	v_lshlrev_b64 v[32:33], 6, v[76:77]
	v_lshl_add_u64 v[32:33], s[46:47], 0, v[32:33]
	v_lshl_add_u64 v[32:33], s[58:59], 2, v[32:33]
	s_lshl_b32 s38, s8, 2
	v_lshl_add_u64 v[32:33], v[32:33], 0, s[38:39]
	flat_store_dword v[32:33], v34 sc0 sc1
.LBB0_431:
	s_or_b64 exec, exec, s[6:7]
	v_add_u32_e32 v48, 0xa0, v166
	v_ashrrev_i32_e32 v49, 31, v48
	v_lshlrev_b64 v[54:55], 11, v[48:49]
	s_waitcnt lgkmcnt(0)
	v_lshl_add_u64 v[32:33], v[168:169], 0, v[54:55]
	global_load_dwordx4 v[50:53], v[32:33], off
	global_load_dwordx4 v[40:43], v[32:33], off offset:256
	v_add_u32_e32 v44, 0xb0, v166
	v_ashrrev_i32_e32 v45, 31, v44
	v_lshlrev_b64 v[46:47], 11, v[44:45]
	v_lshl_add_u64 v[32:33], v[168:169], 0, v[46:47]
	global_load_dwordx4 v[36:39], v[32:33], off
	s_nop 0
	global_load_dwordx4 v[32:35], v[32:33], off offset:256
	s_waitcnt vmcnt(0)
	v_lshlrev_b32_e32 v56, 16, v50
	v_and_b32_e32 v57, 0xffff0000, v50
	v_lshlrev_b32_e32 v50, 16, v51
	v_and_b32_e32 v51, 0xffff0000, v51
	v_lshlrev_b32_e32 v58, 16, v52
	v_and_b32_e32 v59, 0xffff0000, v52
	v_pk_add_f32 v[26:27], v[26:27], v[50:51]
	v_pk_add_f32 v[24:25], v[24:25], v[56:57]
	v_pk_add_f32 v[28:29], v[28:29], v[58:59]
	v_lshlrev_b32_e32 v52, 16, v53
	v_and_b32_e32 v53, 0xffff0000, v53
	v_cvt_pk_bf16_f32 v24, v24, v25
	v_cvt_pk_bf16_f32 v25, v26, v27
	v_cvt_pk_bf16_f32 v26, v28, v29
	v_lshl_add_u64 v[28:29], s[68:69], 0, v[54:55]
	v_pk_add_f32 v[30:31], v[30:31], v[52:53]
	v_lshl_add_u64 v[28:29], v[164:165], 1, v[28:29]
	v_cvt_pk_bf16_f32 v27, v30, v31
	global_store_dwordx4 v[28:29], v[24:27], off nt
	v_lshlrev_b32_e32 v30, 16, v24
	v_and_b32_e32 v31, 0xffff0000, v42
	v_and_b32_e32 v24, 0xffff0000, v24
	v_mul_f32_e32 v24, v24, v24
	v_fmac_f32_e32 v24, v30, v30
	v_lshlrev_b32_e32 v30, 16, v25
	v_and_b32_e32 v25, 0xffff0000, v25
	v_mul_f32_e32 v25, v25, v25
	v_fmac_f32_e32 v25, v30, v30
	v_add_f32_e32 v24, v24, v25
	v_lshlrev_b32_e32 v25, 16, v26
	v_and_b32_e32 v26, 0xffff0000, v26
	v_mul_f32_e32 v26, v26, v26
	v_fmac_f32_e32 v26, v25, v25
	v_add_f32_e32 v24, v24, v26
	v_and_b32_e32 v26, 0xffff0000, v27
	v_lshlrev_b32_e32 v25, 16, v27
	v_mul_f32_e32 v26, v26, v26
	v_fmac_f32_e32 v26, v25, v25
	v_add_f32_e32 v50, v24, v26
	v_lshlrev_b32_e32 v24, 16, v40
	v_and_b32_e32 v25, 0xffff0000, v40
	v_lshlrev_b32_e32 v26, 16, v41
	v_and_b32_e32 v27, 0xffff0000, v41
	v_lshlrev_b32_e32 v30, 16, v42
	v_lshlrev_b32_e32 v40, 16, v43
	v_and_b32_e32 v41, 0xffff0000, v43
	v_pk_add_f32 v[20:21], v[20:21], v[24:25]
	v_pk_add_f32 v[24:25], v[18:19], v[40:41]
	v_pk_add_f32 v[18:19], v[16:17], v[30:31]
	v_cvt_pk_bf16_f32 v16, v20, v21
	v_pk_add_f32 v[22:23], v[22:23], v[26:27]
	v_lshlrev_b32_e32 v20, 16, v16
	v_cvt_pk_bf16_f32 v17, v22, v23
	v_cvt_pk_bf16_f32 v18, v18, v19
	v_cvt_pk_bf16_f32 v19, v24, v25
	global_store_dwordx4 v[28:29], v[16:19], off offset:256 nt
	s_nop 1
	v_and_b32_e32 v16, 0xffff0000, v16
	v_mul_f32_e32 v16, v16, v16
	v_fmac_f32_e32 v16, v20, v20
	v_lshlrev_b32_e32 v20, 16, v17
	v_and_b32_e32 v17, 0xffff0000, v17
	v_mul_f32_e32 v17, v17, v17
	v_add_f32_e32 v16, v50, v16
	v_fmac_f32_e32 v17, v20, v20
	v_add_f32_e32 v16, v16, v17
	v_lshlrev_b32_e32 v17, 16, v18
	v_and_b32_e32 v18, 0xffff0000, v18
	v_mul_f32_e32 v18, v18, v18
	v_fmac_f32_e32 v18, v17, v17
	v_add_f32_e32 v16, v16, v18
	v_and_b32_e32 v18, 0xffff0000, v19
	v_lshlrev_b32_e32 v17, 16, v19
	v_mul_f32_e32 v18, v18, v18
	v_fmac_f32_e32 v18, v17, v17
	v_add_f32_e32 v16, v16, v18
	v_mov_b32_e32 v17, v16
	s_nop 1
	v_permlane16_swap_b32_e32 v17, v16
	s_waitcnt lgkmcnt(0)
	v_add_f32_e32 v16, v16, v17
	v_mov_b32_e32 v17, v16
	s_nop 1
	v_permlane32_swap_b32_e32 v17, v16
	s_and_saveexec_b64 s[6:7], vcc
	s_cbranch_execz .LBB0_433
	s_waitcnt lgkmcnt(0)
	v_add_f32_e32 v18, v16, v17
	v_lshlrev_b64 v[16:17], 6, v[48:49]
	v_lshl_add_u64 v[16:17], s[46:47], 0, v[16:17]
	v_lshl_add_u64 v[16:17], s[58:59], 2, v[16:17]
	s_lshl_b32 s38, s8, 2
	v_lshl_add_u64 v[16:17], v[16:17], 0, s[38:39]
	flat_store_dword v[16:17], v18 sc0 sc1
.LBB0_433:
	s_or_b64 exec, exec, s[6:7]
	v_lshlrev_b32_e32 v16, 16, v36
	s_waitcnt lgkmcnt(0)
	v_and_b32_e32 v17, 0xffff0000, v36
	v_lshlrev_b32_e32 v20, 16, v38
	v_and_b32_e32 v21, 0xffff0000, v38
	v_lshlrev_b32_e32 v22, 16, v39
	v_and_b32_e32 v23, 0xffff0000, v39
	v_pk_add_f32 v[12:13], v[12:13], v[16:17]
	v_lshlrev_b32_e32 v18, 16, v37
	v_and_b32_e32 v19, 0xffff0000, v37
	v_pk_add_f32 v[16:17], v[10:11], v[22:23]
	v_pk_add_f32 v[10:11], v[8:9], v[20:21]
	v_cvt_pk_bf16_f32 v8, v12, v13
	v_lshl_add_u64 v[12:13], s[68:69], 0, v[46:47]
	v_pk_add_f32 v[14:15], v[14:15], v[18:19]
	v_lshl_add_u64 v[12:13], v[164:165], 1, v[12:13]
	v_cvt_pk_bf16_f32 v9, v14, v15
	v_cvt_pk_bf16_f32 v10, v10, v11
	v_cvt_pk_bf16_f32 v11, v16, v17
	global_store_dwordx4 v[12:13], v[8:11], off nt
	v_lshlrev_b32_e32 v14, 16, v8
	v_and_b32_e32 v15, 0xffff0000, v34
	v_and_b32_e32 v8, 0xffff0000, v8
	v_mul_f32_e32 v8, v8, v8
	v_fmac_f32_e32 v8, v14, v14
	v_lshlrev_b32_e32 v14, 16, v9
	v_and_b32_e32 v9, 0xffff0000, v9
	v_mul_f32_e32 v9, v9, v9
	v_fmac_f32_e32 v9, v14, v14
	v_add_f32_e32 v8, v8, v9
	v_lshlrev_b32_e32 v9, 16, v10
	v_and_b32_e32 v10, 0xffff0000, v10
	v_mul_f32_e32 v10, v10, v10
	v_fmac_f32_e32 v10, v9, v9
	v_add_f32_e32 v8, v8, v10
	v_and_b32_e32 v10, 0xffff0000, v11
	v_lshlrev_b32_e32 v9, 16, v11
	v_mul_f32_e32 v10, v10, v10
	v_fmac_f32_e32 v10, v9, v9
	v_add_f32_e32 v18, v8, v10
	v_lshlrev_b32_e32 v8, 16, v32
	v_and_b32_e32 v9, 0xffff0000, v32
	v_lshlrev_b32_e32 v14, 16, v34
	v_lshlrev_b32_e32 v10, 16, v33
	v_and_b32_e32 v11, 0xffff0000, v33
	v_lshlrev_b32_e32 v16, 16, v35
	v_and_b32_e32 v17, 0xffff0000, v35
	v_pk_add_f32 v[4:5], v[4:5], v[8:9]
	v_pk_add_f32 v[0:1], v[0:1], v[14:15]
	v_pk_add_f32 v[6:7], v[6:7], v[10:11]
	v_pk_add_f32 v[8:9], v[2:3], v[16:17]
	v_cvt_pk_bf16_f32 v2, v4, v5
	v_cvt_pk_bf16_f32 v3, v6, v7
	v_cvt_pk_bf16_f32 v4, v0, v1
	s_nop 0
	v_and_b32_e32 v1, 0xffff0000, v2
	v_lshlrev_b32_e32 v0, 16, v2
	v_mul_f32_e32 v1, v1, v1
	v_fmac_f32_e32 v1, v0, v0
	v_and_b32_e32 v6, 0xffff0000, v3
	v_add_f32_e32 v0, v18, v1
	v_lshlrev_b32_e32 v1, 16, v3
	v_mul_f32_e32 v6, v6, v6
	v_fmac_f32_e32 v6, v1, v1
	v_add_f32_e32 v0, v0, v6
	v_and_b32_e32 v6, 0xffff0000, v4
	v_lshlrev_b32_e32 v1, 16, v4
	v_mul_f32_e32 v6, v6, v6
	v_fmac_f32_e32 v6, v1, v1
	v_cvt_pk_bf16_f32 v5, v8, v9
	v_add_f32_e32 v0, v0, v6
	v_and_b32_e32 v6, 0xffff0000, v5
	v_lshlrev_b32_e32 v1, 16, v5
	v_mul_f32_e32 v6, v6, v6
	v_fmac_f32_e32 v6, v1, v1
	v_add_f32_e32 v0, v0, v6
	v_mov_b32_e32 v1, v0
	s_nop 1
	v_permlane16_swap_b32_e32 v1, v0
	global_store_dwordx4 v[12:13], v[2:5], off offset:256 nt
	s_waitcnt lgkmcnt(0)
	v_add_f32_e32 v0, v0, v1
	v_mov_b32_e32 v1, v0
	s_nop 1
	v_permlane32_swap_b32_e32 v1, v0
	s_and_saveexec_b64 s[6:7], vcc
	s_cbranch_execz .LBB0_435
	s_waitcnt lgkmcnt(0)
	v_add_f32_e32 v2, v0, v1
	v_lshlrev_b64 v[0:1], 6, v[44:45]
	v_lshl_add_u64 v[0:1], s[46:47], 0, v[0:1]
	v_lshl_add_u64 v[0:1], s[58:59], 2, v[0:1]
	s_lshl_b32 s38, s8, 2
	v_lshl_add_u64 v[0:1], v[0:1], 0, s[38:39]
	flat_store_dword v[0:1], v2 sc0 sc1
